# mixer wave-offset ordering: waves 0-3 run their attention query blocks first and conv/pool after, waves 4-7 the reverse, so each SIMD holds one matrix-bound and one memory-bound wave (no trailing barr
# speedup vs baseline: 1.0011x; 1.0011x over previous
.LBB0_266:
	s_and_b64 vcc, exec, s[12:13]
	s_cbranch_vccz .LBB0_293
	v_readlane_b32 s10, v253, 7
	v_mov_b32_e32 v76, v241
	v_readlane_b32 s11, v253, 8
	s_and_b64 vcc, exec, s[10:11]
	v_readfirstlane_b32 s6, v76
	s_cbranch_vccz .LBB0_270
	s_and_b64 s[8:9], s[8:9], exec
	s_movk_i32 s8, 0x700
	s_cselect_b32 s10, s8, 0x400
	s_movk_i32 s8, 0xc00
	s_cselect_b32 s8, s8, 0x600
	s_add_u32 s8, s72, s8
	v_readlane_b32 s12, v254, 58
	s_addc_u32 s9, s73, 0
	v_readlane_b32 s13, v254, 59
	s_and_b64 s[12:13], s[12:13], exec
	s_cselect_b32 s11, 0x80000, 0
	v_readlane_b32 s12, v252, 53
	s_add_u32 s12, s12, s11
	v_readlane_b32 s13, v252, 54
	s_addc_u32 s13, s13, 0
	v_readlane_b32 s14, v252, 55
	s_add_u32 s14, s14, s11
	v_readlane_b32 s11, v252, 56
	v_lshlrev_b32_e32 v2, 4, v76
	s_addc_u32 s15, s11, 0
	v_and_b32_e32 v0, 0x70, v2
	v_mov_b32_e32 v1, v185
	v_lshl_add_u64 v[64:65], s[14:15], 0, v[0:1]
	v_add_u32_e32 v1, 0x200, v76
	v_ashrrev_i32_e32 v79, 3, v1
	v_ashrrev_i32_e32 v80, 5, v1
	v_add_u32_e32 v1, 0x400, v76
	v_ashrrev_i32_e32 v81, 3, v1
	v_ashrrev_i32_e32 v82, 5, v1
	v_add_u32_e32 v1, 0x600, v76
	v_and_b32_e32 v15, 64, v243
	v_ashrrev_i32_e32 v83, 3, v1
	v_ashrrev_i32_e32 v84, 5, v1
	v_add_u32_e32 v1, 0, v0
	v_xor_b32_e32 v0, 16, v243
	v_add_u32_e32 v15, 64, v15
	v_cmp_lt_i32_e32 vcc, v0, v15
	s_ashr_i32 s6, s6, 1
	v_and_b32_e32 v4, 63, v76
	v_cndmask_b32_e32 v0, v243, v0, vcc
	v_lshlrev_b32_e32 v85, 2, v0
	v_xor_b32_e32 v0, 32, v243
	v_and_b32_e32 v5, 15, v76
	s_andn2_b32 s6, s6, 31
	v_and_b32_e32 v184, 48, v76
	v_cmp_lt_i32_e32 vcc, v0, v15
	v_bfe_u32 v6, v76, 4, 2
	s_ashr_i32 s11, s6, 31
	v_or_b32_e32 v60, s6, v5
	v_lshl_add_u64 v[62:63], s[8:9], 0, v[184:185]
	v_and_b32_e32 v2, 0x1f0, v2
	v_mov_b32_e32 v3, v185
	v_ashrrev_i32_e32 v77, 3, v76
	v_ashrrev_i32_e32 v78, 5, v76
	s_movk_i32 s6, 0x90
	s_movk_i32 s8, 0x210
	v_cndmask_b32_e32 v0, v243, v0, vcc
	v_or_b32_e32 v16, 48, v4
	v_or_b32_e32 v18, 0x70, v4
	v_or_b32_e32 v19, 0xb0, v4
	v_or_b32_e32 v4, 0xf0, v4
	v_lshl_add_u64 v[66:67], s[12:13], 0, v[2:3]
	v_add_u32_e32 v2, 0, v2
	v_mul_lo_u32 v3, v77, s6
	v_mul_lo_u32 v7, v78, s8
	v_mul_lo_u32 v8, v79, s6
	v_mul_lo_u32 v9, v80, s8
	v_mul_lo_u32 v10, v81, s6
	v_mul_lo_u32 v11, v82, s8
	v_mul_lo_u32 v12, v83, s6
	v_mul_lo_u32 v13, v84, s8
	v_add_u32_e32 v14, 0, v184
	v_lshlrev_b32_e32 v86, 2, v0
	v_lshl_add_u32 v15, v6, 3, 0
	v_lshlrev_b32_e32 v0, 2, v6
	v_mul_u32_u24_e32 v6, 0x90, v5
	v_mul_u32_u24_e32 v17, 0x90, v16
	v_mul_u32_u24_e32 v18, 0x90, v18
	v_mul_u32_u24_e32 v19, 0x90, v19
	v_mul_u32_u24_e32 v4, 0x90, v4
	v_mul_u32_u24_e32 v5, 0x210, v5
	v_mul_u32_u24_e32 v16, 0x210, v16
	v_mov_b32_e32 v61, s11
	v_add_u32_e32 v87, v1, v3
	v_add_u32_e32 v88, v2, v7
	v_add_u32_e32 v89, v1, v8
	v_add_u32_e32 v90, v2, v9
	v_add_u32_e32 v91, v1, v10
	v_add_u32_e32 v92, v2, v11
	v_add_u32_e32 v93, v1, v12
	v_add_u32_e32 v94, v2, v13
	v_add_u32_e32 v95, v14, v6
	v_add_u32_e32 v96, v14, v17
	v_add_u32_e32 v97, v14, v18
	v_add_u32_e32 v98, v14, v19
	v_add_u32_e32 v99, v14, v4
	v_add_u32_e32 v100, v15, v5
	v_add_u32_e32 v101, v15, v16
	v_lshlrev_b32_e32 v184, 1, v0
	v_readlane_b32 s11, v252, 33
	s_mov_b32 s12, s87
	s_cmp_eq_u32 s100, 1
	s_cbranch_scc0 .Latt_nomap
	v_readlane_b32 s6, v252, 0
	s_nop 0
	s_and_b32 s8, s6, 7
	s_lshr_b32 s6, s6, 3
	s_lshr_b32 s13, s8, 1
	s_lshl_b32 s13, s13, 2
	s_lshr_b32 s14, s6, 3
	s_add_i32 s13, s13, s14
	s_lshl_b32 s13, s13, 4
	s_and_b32 s14, s8, 1
	s_lshl_b32 s14, s14, 3
	s_and_b32 s6, s6, 7
	s_add_i32 s14, s14, s6
	s_add_i32 s12, s13, s14
	s_lshl_b32 s11, s12, 9
	s_lshr_b32 s6, s12, 6
	s_bfe_u32 s8, s12, 0x20004
	s_and_b32 s9, s12, 15
	s_lshl_b32 s13, s6, 13
	s_lshl_b32 s14, s9, 9
	s_add_i32 s13, s13, s14
	v_readlane_b32 s14, v254, 58
	v_readlane_b32 s16, v252, 45
	v_readlane_b32 s17, v252, 46
	s_lshl_b32 s70, s8, 7
	s_cmp_lg_u32 s14, 0
	s_cselect_b32 s11, 1, 0
	v_lshrrev_b32_e32 v38, 3, v241
	v_and_b32_e32 v39, 7, v241
	v_lshlrev_b32_e32 v40, 9, v38
	v_lshl_add_u32 v40, v39, 4, v40
	v_bfe_u32 v41, v241, 4, 3
	v_xor_b32_e32 v41, v41, v39
	v_lshlrev_b32_e32 v41, 4, v41
	v_lshl_add_u32 v41, v38, 7, v41
	v_lshrrev_b32_e32 v38, 5, v241
	v_and_b32_e32 v39, 31, v241
	v_lshlrev_b32_e32 v42, 11, v38
	v_lshl_add_u32 v42, v39, 4, v42
	v_mul_u32_u24_e32 v43, 0x210, v38
	v_lshl_add_u32 v43, v39, 4, v43
	s_lshl_b32 s14, s11, 19
	s_add_i32 s14, s14, 0x100000
	s_lshl_b32 s15, s6, 17
	s_add_i32 s14, s14, s15
	s_add_i32 s14, s14, s70
	s_add_u32 s14, s16, s14
	s_addc_u32 s15, s17, 0
	s_lshl_b32 s8, s11, 19
	s_add_i32 s8, s8, 0x200000
	s_lshl_b32 s9, s70, 10
	s_add_i32 s8, s8, s9
	s_lshl_b32 s9, s6, 9
	s_add_i32 s8, s8, s9
	s_add_u32 s8, s16, s8
	s_addc_u32 s9, s17, 0
	global_load_dwordx4 v[78:81], v40, s[14:15]
	global_load_dwordx4 v[94:97], v42, s[8:9]
	s_add_u32 s14, s14, 0x8000
	s_addc_u32 s15, s15, 0
	s_add_u32 s8, s8, 0x8000
	s_addc_u32 s9, s9, 0
	global_load_dwordx4 v[82:85], v40, s[14:15]
	global_load_dwordx4 v[98:101], v42, s[8:9]
	s_add_u32 s14, s14, 0x8000
	s_addc_u32 s15, s15, 0
	s_add_u32 s8, s8, 0x8000
	s_addc_u32 s9, s9, 0
	global_load_dwordx4 v[86:89], v40, s[14:15]
	global_load_dwordx4 v[102:105], v42, s[8:9]
	s_add_u32 s14, s14, 0x8000
	s_addc_u32 s15, s15, 0
	s_add_u32 s8, s8, 0x8000
	s_addc_u32 s9, s9, 0
	global_load_dwordx4 v[90:93], v40, s[14:15]
	global_load_dwordx4 v[106:109], v42, s[8:9]
	v_and_b32_e32 v32, 63, v241
	v_and_b32_e32 v33, 15, v32
	v_lshrrev_b32_e32 v34, 4, v32
	v_lshrrev_b32_e32 v35, 6, v241
	v_lshl_add_u32 v36, v35, 5, v33
	s_cmp_eq_u32 s11, 1
	s_movk_i32 s6, 0xe00
	s_cselect_b32 s6, 0x800, s6
	s_movk_i32 s14, 0xc00
	s_cselect_b32 s14, 0x600, s14
	s_mul_i32 s12, s13, s6
	s_add_i32 s12, s12, s14
	s_add_i32 s12, s12, s70
	s_add_u32 s12, s12, 0xd800000
	s_add_u32 s8, s16, s12
	s_addc_u32 s9, s17, 0
	v_mul_lo_u32 v37, v36, s6
	v_lshl_add_u32 v37, v34, 4, v37
	s_mul_i32 s12, s6, 0
	s_add_u32 s14, s8, s12
	s_addc_u32 s15, s9, 0
	global_load_dwordx4 v[0:3], v37, s[14:15]
	global_load_dwordx4 v[4:7], v37, s[14:15] offset:64
	s_mul_i32 s12, s6, 16
	s_add_u32 s14, s8, s12
	s_addc_u32 s15, s9, 0
	global_load_dwordx4 v[8:11], v37, s[14:15]
	global_load_dwordx4 v[12:15], v37, s[14:15] offset:64
	s_mul_i32 s12, s6, 256
	s_add_u32 s14, s8, s12
	s_addc_u32 s15, s9, 0
	global_load_dwordx4 v[16:19], v37, s[14:15]
	global_load_dwordx4 v[20:23], v37, s[14:15] offset:64
	s_mul_i32 s12, s6, 272
	s_add_u32 s14, s8, s12
	s_addc_u32 s15, s9, 0
	global_load_dwordx4 v[24:27], v37, s[14:15]
	global_load_dwordx4 v[28:31], v37, s[14:15] offset:64
	s_lshl_b32 s12, s13, 11
	s_add_i32 s12, s12, s70
	s_add_u32 s12, s12, 0x9800600
	s_add_u32 s12, s16, s12
	s_addc_u32 s13, s17, 0
	v_bfe_u32 v44, v33, 1, 2
	v_xor_b32_e32 v44, v44, v34
	v_lshrrev_b32_e32 v45, 3, v33
	v_lshl_add_u32 v46, v45, 2, v44
	v_xor_b32_e32 v45, 1, v45
	v_lshl_add_u32 v47, v45, 2, v44
	v_lshlrev_b32_e32 v72, 7, v33
	v_lshl_add_u32 v146, v47, 4, v72
	v_lshl_add_u32 v72, v46, 4, v72
	v_mul_u32_u24_e32 v73, 0x210, v33
	v_lshl_add_u32 v73, v34, 3, v73
	v_lshlrev_b32_e32 v74, 11, v36
	v_lshl_add_u32 v74, v34, 3, v74
	v_mov_b32_e32 v144, 0x3e38aa3b
	v_mov_b32_e32 v145, 0x3e38aa3b
	s_waitcnt vmcnt(8)
	ds_write_b128 v41, v[78:81] offset:0
	ds_write_b128 v43, v[94:97] offset:36864
	ds_write_b128 v41, v[82:85] offset:8192
	ds_write_b128 v43, v[98:101] offset:45312
	ds_write_b128 v41, v[86:89] offset:16384
	ds_write_b128 v43, v[102:105] offset:53760
	ds_write_b128 v41, v[90:93] offset:24576
	ds_write_b128 v43, v[106:109] offset:62208
	s_waitcnt vmcnt(0) lgkmcnt(0)
	s_barrier
	v_readfirstlane_b32 s6, v241
	s_mov_b32 m0, 0
	s_lshr_b32 s6, s6, 6
	s_cmp_lt_u32 s6, 4
	s_cbranch_scc1 .Latt_compute
	s_mov_b32 m0, 0x5a5a5a5a
	s_branch .LBB0_270
.Lmyatt_late:
	v_readlane_b32 s6, v252, 0
	s_nop 0
	s_and_b32 s8, s6, 7
	s_lshr_b32 s6, s6, 3
	s_lshr_b32 s13, s8, 1
	s_lshl_b32 s13, s13, 2
	s_lshr_b32 s14, s6, 3
	s_add_i32 s13, s13, s14
	s_lshl_b32 s13, s13, 4
	s_and_b32 s14, s8, 1
	s_lshl_b32 s14, s14, 3
	s_and_b32 s6, s6, 7
	s_add_i32 s14, s14, s6
	s_add_i32 s12, s13, s14
	s_lshr_b32 s6, s12, 6
	s_bfe_u32 s8, s12, 0x20004
	s_and_b32 s9, s12, 15
	s_lshl_b32 s13, s6, 13
	s_lshl_b32 s14, s9, 9
	s_add_i32 s13, s13, s14
	v_readlane_b32 s14, v254, 58
	v_readlane_b32 s16, v252, 45
	v_readlane_b32 s17, v252, 46
	s_lshl_b32 s70, s8, 7
	s_cmp_lg_u32 s14, 0
	s_cselect_b32 s11, 1, 0
	v_and_b32_e32 v32, 63, v241
	v_and_b32_e32 v33, 15, v32
	v_lshrrev_b32_e32 v34, 4, v32
	v_lshrrev_b32_e32 v35, 6, v241
	v_lshl_add_u32 v36, v35, 5, v33
	s_cmp_eq_u32 s11, 1
	s_movk_i32 s6, 0xe00
	s_cselect_b32 s6, 0x800, s6
	s_movk_i32 s14, 0xc00
	s_cselect_b32 s14, 0x600, s14
	s_mul_i32 s12, s13, s6
	s_add_i32 s12, s12, s14
	s_add_i32 s12, s12, s70
	s_add_u32 s12, s12, 0xd800000
	s_add_u32 s8, s16, s12
	s_addc_u32 s9, s17, 0
	v_mul_lo_u32 v37, v36, s6
	v_lshl_add_u32 v37, v34, 4, v37
	s_mul_i32 s12, s6, 0
	s_add_u32 s14, s8, s12
	s_addc_u32 s15, s9, 0
	global_load_dwordx4 v[0:3], v37, s[14:15]
	global_load_dwordx4 v[4:7], v37, s[14:15] offset:64
	s_mul_i32 s12, s6, 16
	s_add_u32 s14, s8, s12
	s_addc_u32 s15, s9, 0
	global_load_dwordx4 v[8:11], v37, s[14:15]
	global_load_dwordx4 v[12:15], v37, s[14:15] offset:64
	s_mul_i32 s12, s6, 256
	s_add_u32 s14, s8, s12
	s_addc_u32 s15, s9, 0
	global_load_dwordx4 v[16:19], v37, s[14:15]
	global_load_dwordx4 v[20:23], v37, s[14:15] offset:64
	s_mul_i32 s12, s6, 272
	s_add_u32 s14, s8, s12
	s_addc_u32 s15, s9, 0
	global_load_dwordx4 v[24:27], v37, s[14:15]
	global_load_dwordx4 v[28:31], v37, s[14:15] offset:64
	s_lshl_b32 s12, s13, 11
	s_add_i32 s12, s12, s70
	s_add_u32 s12, s12, 0x9800600
	s_add_u32 s12, s16, s12
	s_addc_u32 s13, s17, 0
	v_bfe_u32 v44, v33, 1, 2
	v_xor_b32_e32 v44, v44, v34
	v_lshrrev_b32_e32 v45, 3, v33
	v_lshl_add_u32 v46, v45, 2, v44
	v_xor_b32_e32 v45, 1, v45
	v_lshl_add_u32 v47, v45, 2, v44
	v_lshlrev_b32_e32 v72, 7, v33
	v_lshl_add_u32 v146, v47, 4, v72
	v_lshl_add_u32 v72, v46, 4, v72
	v_mul_u32_u24_e32 v73, 0x210, v33
	v_lshl_add_u32 v73, v34, 3, v73
	v_lshlrev_b32_e32 v74, 11, v36
	v_lshl_add_u32 v74, v34, 3, v74
	v_mov_b32_e32 v144, 0x3e38aa3b
	v_mov_b32_e32 v145, 0x3e38aa3b
	s_waitcnt vmcnt(0)
	s_mov_b32 m0, 0x1234
.Latt_compute:
	ds_read_b128 v[48:51], v72 offset:0
	ds_read_b128 v[52:55], v146 offset:0
	ds_read_b128 v[56:59], v72 offset:2048
	ds_read_b128 v[60:63], v146 offset:2048
	ds_read_b128 v[64:67], v72 offset:4096
	ds_read_b128 v[68:71], v146 offset:4096
	ds_read_b128 v[32:35], v72 offset:6144
	ds_read_b128 v[36:39], v146 offset:6144
	ds_read_b128 v[40:43], v72 offset:8192
	s_waitcnt lgkmcnt(8)
	v_mfma_f32_16x16x32_bf16 v[78:81], v[48:51], v[0:3], 0
	ds_read_b128 v[44:47], v146 offset:8192
	s_waitcnt lgkmcnt(8)
	v_mfma_f32_16x16x32_bf16 v[78:81], v[52:55], v[4:7], v[78:81]
	ds_read_b128 v[48:51], v72 offset:10240
	s_waitcnt lgkmcnt(8)
	v_mfma_f32_16x16x32_bf16 v[82:85], v[56:59], v[0:3], 0
	ds_read_b128 v[52:55], v146 offset:10240
	s_waitcnt lgkmcnt(8)
	v_mfma_f32_16x16x32_bf16 v[82:85], v[60:63], v[4:7], v[82:85]
	ds_read_b128 v[56:59], v72 offset:12288
	s_waitcnt lgkmcnt(8)
	v_mfma_f32_16x16x32_bf16 v[86:89], v[64:67], v[0:3], 0
	ds_read_b128 v[60:63], v146 offset:12288
	s_waitcnt lgkmcnt(8)
	v_mfma_f32_16x16x32_bf16 v[86:89], v[68:71], v[4:7], v[86:89]
	ds_read_b128 v[64:67], v72 offset:14336
	s_waitcnt lgkmcnt(8)
	v_mfma_f32_16x16x32_bf16 v[90:93], v[32:35], v[0:3], 0
	ds_read_b128 v[68:71], v146 offset:14336
	s_waitcnt lgkmcnt(8)
	v_mfma_f32_16x16x32_bf16 v[90:93], v[36:39], v[4:7], v[90:93]
	ds_read_b128 v[32:35], v72 offset:16384
	s_waitcnt lgkmcnt(8)
	v_mfma_f32_16x16x32_bf16 v[94:97], v[40:43], v[0:3], 0
	ds_read_b128 v[36:39], v146 offset:16384
	s_waitcnt lgkmcnt(8)
	v_mfma_f32_16x16x32_bf16 v[94:97], v[44:47], v[4:7], v[94:97]
	ds_read_b128 v[40:43], v72 offset:18432
	s_waitcnt lgkmcnt(8)
	v_mfma_f32_16x16x32_bf16 v[98:101], v[48:51], v[0:3], 0
	ds_read_b128 v[44:47], v146 offset:18432
	s_waitcnt lgkmcnt(8)
	v_mfma_f32_16x16x32_bf16 v[98:101], v[52:55], v[4:7], v[98:101]
	ds_read_b128 v[48:51], v72 offset:20480
	s_waitcnt lgkmcnt(8)
	v_mfma_f32_16x16x32_bf16 v[102:105], v[56:59], v[0:3], 0
	ds_read_b128 v[52:55], v146 offset:20480
	s_waitcnt lgkmcnt(8)
	v_mfma_f32_16x16x32_bf16 v[102:105], v[60:63], v[4:7], v[102:105]
	ds_read_b128 v[56:59], v72 offset:22528
	s_waitcnt lgkmcnt(8)
	v_mfma_f32_16x16x32_bf16 v[106:109], v[64:67], v[0:3], 0
	ds_read_b128 v[60:63], v146 offset:22528
	s_waitcnt lgkmcnt(8)
	v_mfma_f32_16x16x32_bf16 v[106:109], v[68:71], v[4:7], v[106:109]
	ds_read_b128 v[64:67], v72 offset:24576
	s_waitcnt lgkmcnt(8)
	v_mfma_f32_16x16x32_bf16 v[110:113], v[32:35], v[0:3], 0
	ds_read_b128 v[68:71], v146 offset:24576
	s_waitcnt lgkmcnt(8)
	v_mfma_f32_16x16x32_bf16 v[110:113], v[36:39], v[4:7], v[110:113]
	ds_read_b128 v[32:35], v72 offset:26624
	s_waitcnt lgkmcnt(8)
	v_mfma_f32_16x16x32_bf16 v[114:117], v[40:43], v[0:3], 0
	ds_read_b128 v[36:39], v146 offset:26624
	s_waitcnt lgkmcnt(8)
	v_mfma_f32_16x16x32_bf16 v[114:117], v[44:47], v[4:7], v[114:117]
	ds_read_b128 v[40:43], v72 offset:28672
	s_waitcnt lgkmcnt(8)
	v_mfma_f32_16x16x32_bf16 v[118:121], v[48:51], v[0:3], 0
	ds_read_b128 v[44:47], v146 offset:28672
	s_waitcnt lgkmcnt(8)
	v_mfma_f32_16x16x32_bf16 v[118:121], v[52:55], v[4:7], v[118:121]
	ds_read_b128 v[48:51], v72 offset:30720
	s_waitcnt lgkmcnt(8)
	v_mfma_f32_16x16x32_bf16 v[122:125], v[56:59], v[0:3], 0
	ds_read_b128 v[52:55], v146 offset:30720
	s_waitcnt lgkmcnt(8)
	v_mfma_f32_16x16x32_bf16 v[122:125], v[60:63], v[4:7], v[122:125]
	s_waitcnt lgkmcnt(7)
	v_mfma_f32_16x16x32_bf16 v[126:129], v[64:67], v[0:3], 0
	s_waitcnt lgkmcnt(6)
	v_mfma_f32_16x16x32_bf16 v[126:129], v[68:71], v[4:7], v[126:129]
	s_waitcnt lgkmcnt(5)
	v_mfma_f32_16x16x32_bf16 v[130:133], v[32:35], v[0:3], 0
	s_waitcnt lgkmcnt(4)
	v_mfma_f32_16x16x32_bf16 v[130:133], v[36:39], v[4:7], v[130:133]
	s_waitcnt lgkmcnt(3)
	v_mfma_f32_16x16x32_bf16 v[134:137], v[40:43], v[0:3], 0
	s_waitcnt lgkmcnt(2)
	v_mfma_f32_16x16x32_bf16 v[134:137], v[44:47], v[4:7], v[134:137]
	s_waitcnt lgkmcnt(1)
	v_mfma_f32_16x16x32_bf16 v[138:141], v[48:51], v[0:3], 0
	s_waitcnt lgkmcnt(0)
	v_mfma_f32_16x16x32_bf16 v[138:141], v[52:55], v[4:7], v[138:141]
	ds_read_b64 v[48:49], v73 offset:36864
	ds_read_b64 v[50:51], v73 offset:36896
	ds_read_b64 v[52:53], v73 offset:45312
	ds_read_b64 v[54:55], v73 offset:45344
	ds_read_b64 v[56:57], v73 offset:53760
	ds_read_b64 v[58:59], v73 offset:53792
	ds_read_b64 v[60:61], v73 offset:62208
	ds_read_b64 v[62:63], v73 offset:62240
	ds_read_b64 v[64:65], v73 offset:36928
	ds_read_b64 v[66:67], v73 offset:36960
	ds_read_b64 v[68:69], v73 offset:45376
	ds_read_b64 v[70:71], v73 offset:45408
	v_max3_f32 v36, v78, v79, v80
	v_max3_f32 v36, v36, v81, v82
	v_max3_f32 v36, v36, v83, v84
	v_max3_f32 v36, v36, v85, v86
	v_max3_f32 v36, v36, v87, v88
	v_max3_f32 v36, v36, v89, v90
	v_max3_f32 v36, v36, v91, v92
	v_max3_f32 v36, v36, v93, v94
	v_max3_f32 v36, v36, v95, v96
	v_max3_f32 v36, v36, v97, v98
	v_max3_f32 v36, v36, v99, v100
	v_max3_f32 v36, v36, v101, v102
	v_max3_f32 v36, v36, v103, v104
	v_max3_f32 v36, v36, v105, v106
	v_max3_f32 v36, v36, v107, v108
	v_max3_f32 v36, v36, v109, v110
	v_max3_f32 v36, v36, v111, v112
	v_max3_f32 v36, v36, v113, v114
	v_max3_f32 v36, v36, v115, v116
	v_max3_f32 v36, v36, v117, v118
	v_max3_f32 v36, v36, v119, v120
	v_max3_f32 v36, v36, v121, v122
	v_max3_f32 v36, v36, v123, v124
	v_max3_f32 v36, v36, v125, v126
	v_max3_f32 v36, v36, v127, v128
	v_max3_f32 v36, v36, v129, v130
	v_max3_f32 v36, v36, v131, v132
	v_max3_f32 v36, v36, v133, v134
	v_max3_f32 v36, v36, v135, v136
	v_max3_f32 v36, v36, v137, v138
	v_max3_f32 v36, v36, v139, v140
	v_max_f32_e32 v36, v36, v141
	v_mov_b32_e32 v37, v36
	s_nop 1
	v_permlane16_swap_b32_e32 v36, v37
	v_max_f32_e32 v36, v36, v37
	v_mov_b32_e32 v37, v36
	s_nop 1
	v_permlane32_swap_b32_e32 v36, v37
	v_max_f32_e32 v36, v36, v37
	v_mul_f32_e64 v38, v36, -v144
	v_mov_b32_e32 v40, 0
	v_mov_b32_e32 v41, 0
	v_mov_b32_e32 v39, v38
	v_pk_fma_f32 v[78:79], v[78:79], v[144:145], v[38:39]
	v_pk_fma_f32 v[80:81], v[80:81], v[144:145], v[38:39]
	v_exp_f32_e32 v78, v78
	v_exp_f32_e32 v79, v79
	v_exp_f32_e32 v80, v80
	v_exp_f32_e32 v81, v81
	v_pk_fma_f32 v[82:83], v[82:83], v[144:145], v[38:39]
	v_pk_fma_f32 v[84:85], v[84:85], v[144:145], v[38:39]
	v_exp_f32_e32 v82, v82
	v_exp_f32_e32 v83, v83
	v_exp_f32_e32 v84, v84
	v_exp_f32_e32 v85, v85
	v_pk_add_f32 v[40:41], v[40:41], v[78:79]
	v_pk_add_f32 v[40:41], v[40:41], v[80:81]
	v_pk_fma_f32 v[86:87], v[86:87], v[144:145], v[38:39]
	v_pk_fma_f32 v[88:89], v[88:89], v[144:145], v[38:39]
	v_exp_f32_e32 v86, v86
	v_exp_f32_e32 v87, v87
	v_exp_f32_e32 v88, v88
	v_exp_f32_e32 v89, v89
	v_pk_add_f32 v[40:41], v[40:41], v[82:83]
	v_pk_add_f32 v[40:41], v[40:41], v[84:85]
	v_pk_fma_f32 v[90:91], v[90:91], v[144:145], v[38:39]
	v_pk_fma_f32 v[92:93], v[92:93], v[144:145], v[38:39]
	v_exp_f32_e32 v90, v90
	v_exp_f32_e32 v91, v91
	v_exp_f32_e32 v92, v92
	v_exp_f32_e32 v93, v93
	v_pk_add_f32 v[40:41], v[40:41], v[86:87]
	v_pk_add_f32 v[40:41], v[40:41], v[88:89]
	v_pk_fma_f32 v[94:95], v[94:95], v[144:145], v[38:39]
	v_pk_fma_f32 v[96:97], v[96:97], v[144:145], v[38:39]
	v_exp_f32_e32 v94, v94
	v_exp_f32_e32 v95, v95
	v_exp_f32_e32 v96, v96
	v_exp_f32_e32 v97, v97
	v_pk_add_f32 v[40:41], v[40:41], v[90:91]
	v_pk_add_f32 v[40:41], v[40:41], v[92:93]
	v_pk_fma_f32 v[98:99], v[98:99], v[144:145], v[38:39]
	v_pk_fma_f32 v[100:101], v[100:101], v[144:145], v[38:39]
	v_exp_f32_e32 v98, v98
	v_exp_f32_e32 v99, v99
	v_exp_f32_e32 v100, v100
	v_exp_f32_e32 v101, v101
	v_pk_add_f32 v[40:41], v[40:41], v[94:95]
	v_pk_add_f32 v[40:41], v[40:41], v[96:97]
	v_pk_fma_f32 v[102:103], v[102:103], v[144:145], v[38:39]
	v_pk_fma_f32 v[104:105], v[104:105], v[144:145], v[38:39]
	v_exp_f32_e32 v102, v102
	v_exp_f32_e32 v103, v103
	v_exp_f32_e32 v104, v104
	v_exp_f32_e32 v105, v105
	v_pk_add_f32 v[40:41], v[40:41], v[98:99]
	v_pk_add_f32 v[40:41], v[40:41], v[100:101]
	v_pk_fma_f32 v[106:107], v[106:107], v[144:145], v[38:39]
	v_pk_fma_f32 v[108:109], v[108:109], v[144:145], v[38:39]
	v_exp_f32_e32 v106, v106
	v_exp_f32_e32 v107, v107
	v_exp_f32_e32 v108, v108
	v_exp_f32_e32 v109, v109
	v_pk_add_f32 v[40:41], v[40:41], v[102:103]
	v_pk_add_f32 v[40:41], v[40:41], v[104:105]
	v_pk_fma_f32 v[110:111], v[110:111], v[144:145], v[38:39]
	v_pk_fma_f32 v[112:113], v[112:113], v[144:145], v[38:39]
	v_exp_f32_e32 v110, v110
	v_exp_f32_e32 v111, v111
	v_exp_f32_e32 v112, v112
	v_exp_f32_e32 v113, v113
	v_pk_add_f32 v[40:41], v[40:41], v[106:107]
	v_pk_add_f32 v[40:41], v[40:41], v[108:109]
	v_pk_fma_f32 v[114:115], v[114:115], v[144:145], v[38:39]
	v_pk_fma_f32 v[116:117], v[116:117], v[144:145], v[38:39]
	v_exp_f32_e32 v114, v114
	v_exp_f32_e32 v115, v115
	v_exp_f32_e32 v116, v116
	v_exp_f32_e32 v117, v117
	v_pk_add_f32 v[40:41], v[40:41], v[110:111]
	v_pk_add_f32 v[40:41], v[40:41], v[112:113]
	v_pk_fma_f32 v[118:119], v[118:119], v[144:145], v[38:39]
	v_pk_fma_f32 v[120:121], v[120:121], v[144:145], v[38:39]
	v_exp_f32_e32 v118, v118
	v_exp_f32_e32 v119, v119
	v_exp_f32_e32 v120, v120
	v_exp_f32_e32 v121, v121
	v_pk_add_f32 v[40:41], v[40:41], v[114:115]
	v_pk_add_f32 v[40:41], v[40:41], v[116:117]
	v_pk_fma_f32 v[122:123], v[122:123], v[144:145], v[38:39]
	v_pk_fma_f32 v[124:125], v[124:125], v[144:145], v[38:39]
	v_exp_f32_e32 v122, v122
	v_exp_f32_e32 v123, v123
	v_exp_f32_e32 v124, v124
	v_exp_f32_e32 v125, v125
	v_pk_add_f32 v[40:41], v[40:41], v[118:119]
	v_pk_add_f32 v[40:41], v[40:41], v[120:121]
	v_pk_fma_f32 v[126:127], v[126:127], v[144:145], v[38:39]
	v_pk_fma_f32 v[128:129], v[128:129], v[144:145], v[38:39]
	v_exp_f32_e32 v126, v126
	v_exp_f32_e32 v127, v127
	v_exp_f32_e32 v128, v128
	v_exp_f32_e32 v129, v129
	v_pk_add_f32 v[40:41], v[40:41], v[122:123]
	v_pk_add_f32 v[40:41], v[40:41], v[124:125]
	v_pk_fma_f32 v[130:131], v[130:131], v[144:145], v[38:39]
	v_pk_fma_f32 v[132:133], v[132:133], v[144:145], v[38:39]
	v_exp_f32_e32 v130, v130
	v_exp_f32_e32 v131, v131
	v_exp_f32_e32 v132, v132
	v_exp_f32_e32 v133, v133
	v_pk_add_f32 v[40:41], v[40:41], v[126:127]
	v_pk_add_f32 v[40:41], v[40:41], v[128:129]
	v_pk_fma_f32 v[134:135], v[134:135], v[144:145], v[38:39]
	v_pk_fma_f32 v[136:137], v[136:137], v[144:145], v[38:39]
	v_exp_f32_e32 v134, v134
	v_exp_f32_e32 v135, v135
	v_exp_f32_e32 v136, v136
	v_exp_f32_e32 v137, v137
	v_pk_add_f32 v[40:41], v[40:41], v[130:131]
	v_pk_add_f32 v[40:41], v[40:41], v[132:133]
	v_pk_fma_f32 v[138:139], v[138:139], v[144:145], v[38:39]
	v_pk_fma_f32 v[140:141], v[140:141], v[144:145], v[38:39]
	v_exp_f32_e32 v138, v138
	v_exp_f32_e32 v139, v139
	v_exp_f32_e32 v140, v140
	v_exp_f32_e32 v141, v141
	v_pk_add_f32 v[40:41], v[40:41], v[134:135]
	v_pk_add_f32 v[40:41], v[40:41], v[136:137]
	s_nop 0
	v_pk_add_f32 v[40:41], v[40:41], v[138:139]
	v_pk_add_f32 v[40:41], v[40:41], v[140:141]
	v_add_f32_e32 v36, v40, v41
	v_mov_b32_e32 v37, v36
	s_nop 1
	v_permlane16_swap_b32_e32 v36, v37
	v_add_f32_e32 v36, v36, v37
	v_mov_b32_e32 v37, v36
	s_nop 1
	v_permlane32_swap_b32_e32 v36, v37
	v_add_f32_e32 v36, v36, v37
	v_rcp_f32_e32 v142, v36
	v_cvt_pk_bf16_f32 v78, v78, v79
	v_cvt_pk_bf16_f32 v79, v80, v81
	v_cvt_pk_bf16_f32 v80, v82, v83
	v_cvt_pk_bf16_f32 v81, v84, v85
	v_cvt_pk_bf16_f32 v86, v86, v87
	v_cvt_pk_bf16_f32 v87, v88, v89
	v_cvt_pk_bf16_f32 v88, v90, v91
	v_cvt_pk_bf16_f32 v89, v92, v93
	v_cvt_pk_bf16_f32 v94, v94, v95
	v_cvt_pk_bf16_f32 v95, v96, v97
	v_cvt_pk_bf16_f32 v96, v98, v99
	v_cvt_pk_bf16_f32 v97, v100, v101
	v_cvt_pk_bf16_f32 v102, v102, v103
	v_cvt_pk_bf16_f32 v103, v104, v105
	v_cvt_pk_bf16_f32 v104, v106, v107
	v_cvt_pk_bf16_f32 v105, v108, v109
	v_cvt_pk_bf16_f32 v110, v110, v111
	v_cvt_pk_bf16_f32 v111, v112, v113
	v_cvt_pk_bf16_f32 v112, v114, v115
	v_cvt_pk_bf16_f32 v113, v116, v117
	v_cvt_pk_bf16_f32 v118, v118, v119
	v_cvt_pk_bf16_f32 v119, v120, v121
	v_cvt_pk_bf16_f32 v120, v122, v123
	v_cvt_pk_bf16_f32 v121, v124, v125
	v_cvt_pk_bf16_f32 v126, v126, v127
	v_cvt_pk_bf16_f32 v127, v128, v129
	v_cvt_pk_bf16_f32 v128, v130, v131
	v_cvt_pk_bf16_f32 v129, v132, v133
	v_cvt_pk_bf16_f32 v134, v134, v135
	v_cvt_pk_bf16_f32 v135, v136, v137
	v_cvt_pk_bf16_f32 v136, v138, v139
	v_cvt_pk_bf16_f32 v137, v140, v141
	v_fma_f32 v143, -v36, v142, 1.0
	v_fma_f32 v142, v143, v142, v142
	v_mov_b32_e32 v143, v142
	ds_read_b64 v[82:83], v73 offset:53824
	ds_read_b64 v[84:85], v73 offset:53856
	s_waitcnt lgkmcnt(12)
	v_mfma_f32_16x16x32_bf16 v[32:35], v[48:51], v[78:81], 0
	ds_read_b64 v[90:91], v73 offset:62272
	ds_read_b64 v[92:93], v73 offset:62304
	s_waitcnt lgkmcnt(12)
	v_mfma_f32_16x16x32_bf16 v[36:39], v[52:55], v[78:81], 0
	ds_read_b64 v[48:49], v73 offset:36992
	ds_read_b64 v[50:51], v73 offset:37024
	s_waitcnt lgkmcnt(12)
	v_mfma_f32_16x16x32_bf16 v[40:43], v[56:59], v[78:81], 0
	ds_read_b64 v[52:53], v73 offset:45440
	ds_read_b64 v[54:55], v73 offset:45472
	s_waitcnt lgkmcnt(12)
	v_mfma_f32_16x16x32_bf16 v[44:47], v[60:63], v[78:81], 0
	ds_read_b64 v[56:57], v73 offset:53888
	ds_read_b64 v[58:59], v73 offset:53920
	s_waitcnt lgkmcnt(12)
	v_mfma_f32_16x16x32_bf16 v[32:35], v[64:67], v[86:89], v[32:35]
	ds_read_b64 v[60:61], v73 offset:62336
	ds_read_b64 v[62:63], v73 offset:62368
	s_waitcnt lgkmcnt(12)
	v_mfma_f32_16x16x32_bf16 v[36:39], v[68:71], v[86:89], v[36:39]
	ds_read_b64 v[64:65], v73 offset:37056
	ds_read_b64 v[66:67], v73 offset:37088
	s_waitcnt lgkmcnt(12)
	v_mfma_f32_16x16x32_bf16 v[40:43], v[82:85], v[86:89], v[40:43]
	ds_read_b64 v[68:69], v73 offset:45504
	ds_read_b64 v[70:71], v73 offset:45536
	s_waitcnt lgkmcnt(12)
	v_mfma_f32_16x16x32_bf16 v[44:47], v[90:93], v[86:89], v[44:47]
	ds_read_b64 v[82:83], v73 offset:53952
	ds_read_b64 v[84:85], v73 offset:53984
	s_waitcnt lgkmcnt(12)
	v_mfma_f32_16x16x32_bf16 v[32:35], v[48:51], v[94:97], v[32:35]
	ds_read_b64 v[90:91], v73 offset:62400
	ds_read_b64 v[92:93], v73 offset:62432
	s_waitcnt lgkmcnt(12)
	v_mfma_f32_16x16x32_bf16 v[36:39], v[52:55], v[94:97], v[36:39]
	ds_read_b64 v[48:49], v73 offset:37120
	ds_read_b64 v[50:51], v73 offset:37152
	s_waitcnt lgkmcnt(12)
	v_mfma_f32_16x16x32_bf16 v[40:43], v[56:59], v[94:97], v[40:43]
	ds_read_b64 v[52:53], v73 offset:45568
	ds_read_b64 v[54:55], v73 offset:45600
	s_waitcnt lgkmcnt(12)
	v_mfma_f32_16x16x32_bf16 v[44:47], v[60:63], v[94:97], v[44:47]
	ds_read_b64 v[56:57], v73 offset:54016
	ds_read_b64 v[58:59], v73 offset:54048
	s_waitcnt lgkmcnt(12)
	v_mfma_f32_16x16x32_bf16 v[32:35], v[64:67], v[102:105], v[32:35]
	ds_read_b64 v[60:61], v73 offset:62464
	ds_read_b64 v[62:63], v73 offset:62496
	s_waitcnt lgkmcnt(12)
	v_mfma_f32_16x16x32_bf16 v[36:39], v[68:71], v[102:105], v[36:39]
	ds_read_b64 v[64:65], v73 offset:37184
	ds_read_b64 v[66:67], v73 offset:37216
	s_waitcnt lgkmcnt(12)
	v_mfma_f32_16x16x32_bf16 v[40:43], v[82:85], v[102:105], v[40:43]
	ds_read_b64 v[68:69], v73 offset:45632
	ds_read_b64 v[70:71], v73 offset:45664
	s_waitcnt lgkmcnt(12)
	v_mfma_f32_16x16x32_bf16 v[44:47], v[90:93], v[102:105], v[44:47]
	ds_read_b64 v[82:83], v73 offset:54080
	ds_read_b64 v[84:85], v73 offset:54112
	s_waitcnt lgkmcnt(12)
	v_mfma_f32_16x16x32_bf16 v[32:35], v[48:51], v[110:113], v[32:35]
	ds_read_b64 v[90:91], v73 offset:62528
	ds_read_b64 v[92:93], v73 offset:62560
	s_waitcnt lgkmcnt(12)
	v_mfma_f32_16x16x32_bf16 v[36:39], v[52:55], v[110:113], v[36:39]
	ds_read_b64 v[48:49], v73 offset:37248
	ds_read_b64 v[50:51], v73 offset:37280
	s_waitcnt lgkmcnt(12)
	v_mfma_f32_16x16x32_bf16 v[40:43], v[56:59], v[110:113], v[40:43]
	ds_read_b64 v[52:53], v73 offset:45696
	ds_read_b64 v[54:55], v73 offset:45728
	s_waitcnt lgkmcnt(12)
	v_mfma_f32_16x16x32_bf16 v[44:47], v[60:63], v[110:113], v[44:47]
	ds_read_b64 v[56:57], v73 offset:54144
	ds_read_b64 v[58:59], v73 offset:54176
	s_waitcnt lgkmcnt(12)
	v_mfma_f32_16x16x32_bf16 v[32:35], v[64:67], v[118:121], v[32:35]
	ds_read_b64 v[60:61], v73 offset:62592
	ds_read_b64 v[62:63], v73 offset:62624
	s_waitcnt lgkmcnt(12)
	v_mfma_f32_16x16x32_bf16 v[36:39], v[68:71], v[118:121], v[36:39]
	ds_read_b64 v[64:65], v73 offset:37312
	ds_read_b64 v[66:67], v73 offset:37344
	s_waitcnt lgkmcnt(12)
	v_mfma_f32_16x16x32_bf16 v[40:43], v[82:85], v[118:121], v[40:43]
	ds_read_b64 v[68:69], v73 offset:45760
	ds_read_b64 v[70:71], v73 offset:45792
	s_waitcnt lgkmcnt(12)
	v_mfma_f32_16x16x32_bf16 v[44:47], v[90:93], v[118:121], v[44:47]
	ds_read_b64 v[82:83], v73 offset:54208
	ds_read_b64 v[84:85], v73 offset:54240
	s_waitcnt lgkmcnt(12)
	v_mfma_f32_16x16x32_bf16 v[32:35], v[48:51], v[126:129], v[32:35]
	ds_read_b64 v[90:91], v73 offset:62656
	ds_read_b64 v[92:93], v73 offset:62688
	s_waitcnt lgkmcnt(12)
	v_mfma_f32_16x16x32_bf16 v[36:39], v[52:55], v[126:129], v[36:39]
	s_waitcnt lgkmcnt(10)
	v_mfma_f32_16x16x32_bf16 v[40:43], v[56:59], v[126:129], v[40:43]
	s_waitcnt lgkmcnt(8)
	v_mfma_f32_16x16x32_bf16 v[44:47], v[60:63], v[126:129], v[44:47]
	s_waitcnt lgkmcnt(6)
	v_mfma_f32_16x16x32_bf16 v[32:35], v[64:67], v[134:137], v[32:35]
	s_waitcnt lgkmcnt(4)
	v_mfma_f32_16x16x32_bf16 v[36:39], v[68:71], v[134:137], v[36:39]
	s_waitcnt lgkmcnt(2)
	v_mfma_f32_16x16x32_bf16 v[40:43], v[82:85], v[134:137], v[40:43]
	s_waitcnt lgkmcnt(0)
	v_mfma_f32_16x16x32_bf16 v[44:47], v[90:93], v[134:137], v[44:47]
	ds_read_b128 v[48:51], v72 offset:0
	ds_read_b128 v[52:55], v146 offset:0
	ds_read_b128 v[56:59], v72 offset:2048
	ds_read_b128 v[60:63], v146 offset:2048
	ds_read_b128 v[64:67], v72 offset:4096
	ds_read_b128 v[68:71], v146 offset:4096
	s_add_u32 s16, s12, 0x0
	s_addc_u32 s17, s13, 0
	s_nop 7
	v_pk_mul_f32 v[32:33], v[32:33], v[142:143]
	v_pk_mul_f32 v[34:35], v[34:35], v[142:143]
	v_pk_mul_f32 v[36:37], v[36:37], v[142:143]
	v_pk_mul_f32 v[38:39], v[38:39], v[142:143]
	v_pk_mul_f32 v[40:41], v[40:41], v[142:143]
	v_pk_mul_f32 v[42:43], v[42:43], v[142:143]
	v_pk_mul_f32 v[44:45], v[44:45], v[142:143]
	v_pk_mul_f32 v[46:47], v[46:47], v[142:143]
	v_cvt_pk_bf16_f32 v32, v32, v33
	v_cvt_pk_bf16_f32 v33, v34, v35
	v_cvt_pk_bf16_f32 v36, v36, v37
	v_cvt_pk_bf16_f32 v37, v38, v39
	v_cvt_pk_bf16_f32 v40, v40, v41
	v_cvt_pk_bf16_f32 v41, v42, v43
	v_cvt_pk_bf16_f32 v44, v44, v45
	v_cvt_pk_bf16_f32 v45, v46, v47
	global_store_dwordx2 v74, v[32:33], s[16:17] offset:0
	global_store_dwordx2 v74, v[36:37], s[16:17] offset:32
	global_store_dwordx2 v74, v[40:41], s[16:17] offset:64
	global_store_dwordx2 v74, v[44:45], s[16:17] offset:96
	ds_read_b128 v[32:35], v72 offset:6144
	ds_read_b128 v[36:39], v146 offset:6144
	ds_read_b128 v[40:43], v72 offset:8192
	s_waitcnt lgkmcnt(8)
	v_mfma_f32_16x16x32_bf16 v[78:81], v[48:51], v[8:11], 0
	ds_read_b128 v[44:47], v146 offset:8192
	s_waitcnt lgkmcnt(8)
	v_mfma_f32_16x16x32_bf16 v[78:81], v[52:55], v[12:15], v[78:81]
	ds_read_b128 v[48:51], v72 offset:10240
	s_waitcnt lgkmcnt(8)
	v_mfma_f32_16x16x32_bf16 v[82:85], v[56:59], v[8:11], 0
	ds_read_b128 v[52:55], v146 offset:10240
	s_waitcnt lgkmcnt(8)
	v_mfma_f32_16x16x32_bf16 v[82:85], v[60:63], v[12:15], v[82:85]
	ds_read_b128 v[56:59], v72 offset:12288
	s_waitcnt lgkmcnt(8)
	v_mfma_f32_16x16x32_bf16 v[86:89], v[64:67], v[8:11], 0
	ds_read_b128 v[60:63], v146 offset:12288
	s_waitcnt lgkmcnt(8)
	v_mfma_f32_16x16x32_bf16 v[86:89], v[68:71], v[12:15], v[86:89]
	ds_read_b128 v[64:67], v72 offset:14336
	s_waitcnt lgkmcnt(8)
	v_mfma_f32_16x16x32_bf16 v[90:93], v[32:35], v[8:11], 0
	ds_read_b128 v[68:71], v146 offset:14336
	s_waitcnt lgkmcnt(8)
	v_mfma_f32_16x16x32_bf16 v[90:93], v[36:39], v[12:15], v[90:93]
	ds_read_b128 v[32:35], v72 offset:16384
	s_waitcnt lgkmcnt(8)
	v_mfma_f32_16x16x32_bf16 v[94:97], v[40:43], v[8:11], 0
	ds_read_b128 v[36:39], v146 offset:16384
	s_waitcnt lgkmcnt(8)
	v_mfma_f32_16x16x32_bf16 v[94:97], v[44:47], v[12:15], v[94:97]
	ds_read_b128 v[40:43], v72 offset:18432
	s_waitcnt lgkmcnt(8)
	v_mfma_f32_16x16x32_bf16 v[98:101], v[48:51], v[8:11], 0
	ds_read_b128 v[44:47], v146 offset:18432
	s_waitcnt lgkmcnt(8)
	v_mfma_f32_16x16x32_bf16 v[98:101], v[52:55], v[12:15], v[98:101]
	ds_read_b128 v[48:51], v72 offset:20480
	s_waitcnt lgkmcnt(8)
	v_mfma_f32_16x16x32_bf16 v[102:105], v[56:59], v[8:11], 0
	ds_read_b128 v[52:55], v146 offset:20480
	s_waitcnt lgkmcnt(8)
	v_mfma_f32_16x16x32_bf16 v[102:105], v[60:63], v[12:15], v[102:105]
	ds_read_b128 v[56:59], v72 offset:22528
	s_waitcnt lgkmcnt(8)
	v_mfma_f32_16x16x32_bf16 v[106:109], v[64:67], v[8:11], 0
	ds_read_b128 v[60:63], v146 offset:22528
	s_waitcnt lgkmcnt(8)
	v_mfma_f32_16x16x32_bf16 v[106:109], v[68:71], v[12:15], v[106:109]
	ds_read_b128 v[64:67], v72 offset:24576
	s_waitcnt lgkmcnt(8)
	v_mfma_f32_16x16x32_bf16 v[110:113], v[32:35], v[8:11], 0
	ds_read_b128 v[68:71], v146 offset:24576
	s_waitcnt lgkmcnt(8)
	v_mfma_f32_16x16x32_bf16 v[110:113], v[36:39], v[12:15], v[110:113]
	ds_read_b128 v[32:35], v72 offset:26624
	s_waitcnt lgkmcnt(8)
	v_mfma_f32_16x16x32_bf16 v[114:117], v[40:43], v[8:11], 0
	ds_read_b128 v[36:39], v146 offset:26624
	s_waitcnt lgkmcnt(8)
	v_mfma_f32_16x16x32_bf16 v[114:117], v[44:47], v[12:15], v[114:117]
	ds_read_b128 v[40:43], v72 offset:28672
	s_waitcnt lgkmcnt(8)
	v_mfma_f32_16x16x32_bf16 v[118:121], v[48:51], v[8:11], 0
	ds_read_b128 v[44:47], v146 offset:28672
	s_waitcnt lgkmcnt(8)
	v_mfma_f32_16x16x32_bf16 v[118:121], v[52:55], v[12:15], v[118:121]
	ds_read_b128 v[48:51], v72 offset:30720
	s_waitcnt lgkmcnt(8)
	v_mfma_f32_16x16x32_bf16 v[122:125], v[56:59], v[8:11], 0
	ds_read_b128 v[52:55], v146 offset:30720
	s_waitcnt lgkmcnt(8)
	v_mfma_f32_16x16x32_bf16 v[122:125], v[60:63], v[12:15], v[122:125]
	s_waitcnt lgkmcnt(7)
	v_mfma_f32_16x16x32_bf16 v[126:129], v[64:67], v[8:11], 0
	s_waitcnt lgkmcnt(6)
	v_mfma_f32_16x16x32_bf16 v[126:129], v[68:71], v[12:15], v[126:129]
	s_waitcnt lgkmcnt(5)
	v_mfma_f32_16x16x32_bf16 v[130:133], v[32:35], v[8:11], 0
	s_waitcnt lgkmcnt(4)
	v_mfma_f32_16x16x32_bf16 v[130:133], v[36:39], v[12:15], v[130:133]
	s_waitcnt lgkmcnt(3)
	v_mfma_f32_16x16x32_bf16 v[134:137], v[40:43], v[8:11], 0
	s_waitcnt lgkmcnt(2)
	v_mfma_f32_16x16x32_bf16 v[134:137], v[44:47], v[12:15], v[134:137]
	s_waitcnt lgkmcnt(1)
	v_mfma_f32_16x16x32_bf16 v[138:141], v[48:51], v[8:11], 0
	s_waitcnt lgkmcnt(0)
	v_mfma_f32_16x16x32_bf16 v[138:141], v[52:55], v[12:15], v[138:141]
	ds_read_b64 v[48:49], v73 offset:36864
	ds_read_b64 v[50:51], v73 offset:36896
	ds_read_b64 v[52:53], v73 offset:45312
	ds_read_b64 v[54:55], v73 offset:45344
	ds_read_b64 v[56:57], v73 offset:53760
	ds_read_b64 v[58:59], v73 offset:53792
	ds_read_b64 v[60:61], v73 offset:62208
	ds_read_b64 v[62:63], v73 offset:62240
	ds_read_b64 v[64:65], v73 offset:36928
	ds_read_b64 v[66:67], v73 offset:36960
	ds_read_b64 v[68:69], v73 offset:45376
	ds_read_b64 v[70:71], v73 offset:45408
	v_max3_f32 v36, v78, v79, v80
	v_max3_f32 v36, v36, v81, v82
	v_max3_f32 v36, v36, v83, v84
	v_max3_f32 v36, v36, v85, v86
	v_max3_f32 v36, v36, v87, v88
	v_max3_f32 v36, v36, v89, v90
	v_max3_f32 v36, v36, v91, v92
	v_max3_f32 v36, v36, v93, v94
	v_max3_f32 v36, v36, v95, v96
	v_max3_f32 v36, v36, v97, v98
	v_max3_f32 v36, v36, v99, v100
	v_max3_f32 v36, v36, v101, v102
	v_max3_f32 v36, v36, v103, v104
	v_max3_f32 v36, v36, v105, v106
	v_max3_f32 v36, v36, v107, v108
	v_max3_f32 v36, v36, v109, v110
	v_max3_f32 v36, v36, v111, v112
	v_max3_f32 v36, v36, v113, v114
	v_max3_f32 v36, v36, v115, v116
	v_max3_f32 v36, v36, v117, v118
	v_max3_f32 v36, v36, v119, v120
	v_max3_f32 v36, v36, v121, v122
	v_max3_f32 v36, v36, v123, v124
	v_max3_f32 v36, v36, v125, v126
	v_max3_f32 v36, v36, v127, v128
	v_max3_f32 v36, v36, v129, v130
	v_max3_f32 v36, v36, v131, v132
	v_max3_f32 v36, v36, v133, v134
	v_max3_f32 v36, v36, v135, v136
	v_max3_f32 v36, v36, v137, v138
	v_max3_f32 v36, v36, v139, v140
	v_max_f32_e32 v36, v36, v141
	v_mov_b32_e32 v37, v36
	s_nop 1
	v_permlane16_swap_b32_e32 v36, v37
	v_max_f32_e32 v36, v36, v37
	v_mov_b32_e32 v37, v36
	s_nop 1
	v_permlane32_swap_b32_e32 v36, v37
	v_max_f32_e32 v36, v36, v37
	v_mul_f32_e64 v38, v36, -v144
	v_mov_b32_e32 v40, 0
	v_mov_b32_e32 v41, 0
	v_mov_b32_e32 v39, v38
	v_pk_fma_f32 v[78:79], v[78:79], v[144:145], v[38:39]
	v_pk_fma_f32 v[80:81], v[80:81], v[144:145], v[38:39]
	v_exp_f32_e32 v78, v78
	v_exp_f32_e32 v79, v79
	v_exp_f32_e32 v80, v80
	v_exp_f32_e32 v81, v81
	v_pk_fma_f32 v[82:83], v[82:83], v[144:145], v[38:39]
	v_pk_fma_f32 v[84:85], v[84:85], v[144:145], v[38:39]
	v_exp_f32_e32 v82, v82
	v_exp_f32_e32 v83, v83
	v_exp_f32_e32 v84, v84
	v_exp_f32_e32 v85, v85
	v_pk_add_f32 v[40:41], v[40:41], v[78:79]
	v_pk_add_f32 v[40:41], v[40:41], v[80:81]
	v_pk_fma_f32 v[86:87], v[86:87], v[144:145], v[38:39]
	v_pk_fma_f32 v[88:89], v[88:89], v[144:145], v[38:39]
	v_exp_f32_e32 v86, v86
	v_exp_f32_e32 v87, v87
	v_exp_f32_e32 v88, v88
	v_exp_f32_e32 v89, v89
	v_pk_add_f32 v[40:41], v[40:41], v[82:83]
	v_pk_add_f32 v[40:41], v[40:41], v[84:85]
	v_pk_fma_f32 v[90:91], v[90:91], v[144:145], v[38:39]
	v_pk_fma_f32 v[92:93], v[92:93], v[144:145], v[38:39]
	v_exp_f32_e32 v90, v90
	v_exp_f32_e32 v91, v91
	v_exp_f32_e32 v92, v92
	v_exp_f32_e32 v93, v93
	v_pk_add_f32 v[40:41], v[40:41], v[86:87]
	v_pk_add_f32 v[40:41], v[40:41], v[88:89]
	v_pk_fma_f32 v[94:95], v[94:95], v[144:145], v[38:39]
	v_pk_fma_f32 v[96:97], v[96:97], v[144:145], v[38:39]
	v_exp_f32_e32 v94, v94
	v_exp_f32_e32 v95, v95
	v_exp_f32_e32 v96, v96
	v_exp_f32_e32 v97, v97
	v_pk_add_f32 v[40:41], v[40:41], v[90:91]
	v_pk_add_f32 v[40:41], v[40:41], v[92:93]
	v_pk_fma_f32 v[98:99], v[98:99], v[144:145], v[38:39]
	v_pk_fma_f32 v[100:101], v[100:101], v[144:145], v[38:39]
	v_exp_f32_e32 v98, v98
	v_exp_f32_e32 v99, v99
	v_exp_f32_e32 v100, v100
	v_exp_f32_e32 v101, v101
	v_pk_add_f32 v[40:41], v[40:41], v[94:95]
	v_pk_add_f32 v[40:41], v[40:41], v[96:97]
	v_pk_fma_f32 v[102:103], v[102:103], v[144:145], v[38:39]
	v_pk_fma_f32 v[104:105], v[104:105], v[144:145], v[38:39]
	v_exp_f32_e32 v102, v102
	v_exp_f32_e32 v103, v103
	v_exp_f32_e32 v104, v104
	v_exp_f32_e32 v105, v105
	v_pk_add_f32 v[40:41], v[40:41], v[98:99]
	v_pk_add_f32 v[40:41], v[40:41], v[100:101]
	v_pk_fma_f32 v[106:107], v[106:107], v[144:145], v[38:39]
	v_pk_fma_f32 v[108:109], v[108:109], v[144:145], v[38:39]
	v_exp_f32_e32 v106, v106
	v_exp_f32_e32 v107, v107
	v_exp_f32_e32 v108, v108
	v_exp_f32_e32 v109, v109
	v_pk_add_f32 v[40:41], v[40:41], v[102:103]
	v_pk_add_f32 v[40:41], v[40:41], v[104:105]
	v_pk_fma_f32 v[110:111], v[110:111], v[144:145], v[38:39]
	v_pk_fma_f32 v[112:113], v[112:113], v[144:145], v[38:39]
	v_exp_f32_e32 v110, v110
	v_exp_f32_e32 v111, v111
	v_exp_f32_e32 v112, v112
	v_exp_f32_e32 v113, v113
	v_pk_add_f32 v[40:41], v[40:41], v[106:107]
	v_pk_add_f32 v[40:41], v[40:41], v[108:109]
	v_pk_fma_f32 v[114:115], v[114:115], v[144:145], v[38:39]
	v_pk_fma_f32 v[116:117], v[116:117], v[144:145], v[38:39]
	v_exp_f32_e32 v114, v114
	v_exp_f32_e32 v115, v115
	v_exp_f32_e32 v116, v116
	v_exp_f32_e32 v117, v117
	v_pk_add_f32 v[40:41], v[40:41], v[110:111]
	v_pk_add_f32 v[40:41], v[40:41], v[112:113]
	v_pk_fma_f32 v[118:119], v[118:119], v[144:145], v[38:39]
	v_pk_fma_f32 v[120:121], v[120:121], v[144:145], v[38:39]
	v_exp_f32_e32 v118, v118
	v_exp_f32_e32 v119, v119
	v_exp_f32_e32 v120, v120
	v_exp_f32_e32 v121, v121
	v_pk_add_f32 v[40:41], v[40:41], v[114:115]
	v_pk_add_f32 v[40:41], v[40:41], v[116:117]
	v_pk_fma_f32 v[122:123], v[122:123], v[144:145], v[38:39]
	v_pk_fma_f32 v[124:125], v[124:125], v[144:145], v[38:39]
	v_exp_f32_e32 v122, v122
	v_exp_f32_e32 v123, v123
	v_exp_f32_e32 v124, v124
	v_exp_f32_e32 v125, v125
	v_pk_add_f32 v[40:41], v[40:41], v[118:119]
	v_pk_add_f32 v[40:41], v[40:41], v[120:121]
	v_pk_fma_f32 v[126:127], v[126:127], v[144:145], v[38:39]
	v_pk_fma_f32 v[128:129], v[128:129], v[144:145], v[38:39]
	v_exp_f32_e32 v126, v126
	v_exp_f32_e32 v127, v127
	v_exp_f32_e32 v128, v128
	v_exp_f32_e32 v129, v129
	v_pk_add_f32 v[40:41], v[40:41], v[122:123]
	v_pk_add_f32 v[40:41], v[40:41], v[124:125]
	v_pk_fma_f32 v[130:131], v[130:131], v[144:145], v[38:39]
	v_pk_fma_f32 v[132:133], v[132:133], v[144:145], v[38:39]
	v_exp_f32_e32 v130, v130
	v_exp_f32_e32 v131, v131
	v_exp_f32_e32 v132, v132
	v_exp_f32_e32 v133, v133
	v_pk_add_f32 v[40:41], v[40:41], v[126:127]
	v_pk_add_f32 v[40:41], v[40:41], v[128:129]
	v_pk_fma_f32 v[134:135], v[134:135], v[144:145], v[38:39]
	v_pk_fma_f32 v[136:137], v[136:137], v[144:145], v[38:39]
	v_exp_f32_e32 v134, v134
	v_exp_f32_e32 v135, v135
	v_exp_f32_e32 v136, v136
	v_exp_f32_e32 v137, v137
	v_pk_add_f32 v[40:41], v[40:41], v[130:131]
	v_pk_add_f32 v[40:41], v[40:41], v[132:133]
	v_pk_fma_f32 v[138:139], v[138:139], v[144:145], v[38:39]
	v_pk_fma_f32 v[140:141], v[140:141], v[144:145], v[38:39]
	v_exp_f32_e32 v138, v138
	v_exp_f32_e32 v139, v139
	v_exp_f32_e32 v140, v140
	v_exp_f32_e32 v141, v141
	v_pk_add_f32 v[40:41], v[40:41], v[134:135]
	v_pk_add_f32 v[40:41], v[40:41], v[136:137]
	s_nop 0
	v_pk_add_f32 v[40:41], v[40:41], v[138:139]
	v_pk_add_f32 v[40:41], v[40:41], v[140:141]
	v_add_f32_e32 v36, v40, v41
	v_mov_b32_e32 v37, v36
	s_nop 1
	v_permlane16_swap_b32_e32 v36, v37
	v_add_f32_e32 v36, v36, v37
	v_mov_b32_e32 v37, v36
	s_nop 1
	v_permlane32_swap_b32_e32 v36, v37
	v_add_f32_e32 v36, v36, v37
	v_rcp_f32_e32 v142, v36
	v_cvt_pk_bf16_f32 v78, v78, v79
	v_cvt_pk_bf16_f32 v79, v80, v81
	v_cvt_pk_bf16_f32 v80, v82, v83
	v_cvt_pk_bf16_f32 v81, v84, v85
	v_cvt_pk_bf16_f32 v86, v86, v87
	v_cvt_pk_bf16_f32 v87, v88, v89
	v_cvt_pk_bf16_f32 v88, v90, v91
	v_cvt_pk_bf16_f32 v89, v92, v93
	v_cvt_pk_bf16_f32 v94, v94, v95
	v_cvt_pk_bf16_f32 v95, v96, v97
	v_cvt_pk_bf16_f32 v96, v98, v99
	v_cvt_pk_bf16_f32 v97, v100, v101
	v_cvt_pk_bf16_f32 v102, v102, v103
	v_cvt_pk_bf16_f32 v103, v104, v105
	v_cvt_pk_bf16_f32 v104, v106, v107
	v_cvt_pk_bf16_f32 v105, v108, v109
	v_cvt_pk_bf16_f32 v110, v110, v111
	v_cvt_pk_bf16_f32 v111, v112, v113
	v_cvt_pk_bf16_f32 v112, v114, v115
	v_cvt_pk_bf16_f32 v113, v116, v117
	v_cvt_pk_bf16_f32 v118, v118, v119
	v_cvt_pk_bf16_f32 v119, v120, v121
	v_cvt_pk_bf16_f32 v120, v122, v123
	v_cvt_pk_bf16_f32 v121, v124, v125
	v_cvt_pk_bf16_f32 v126, v126, v127
	v_cvt_pk_bf16_f32 v127, v128, v129
	v_cvt_pk_bf16_f32 v128, v130, v131
	v_cvt_pk_bf16_f32 v129, v132, v133
	v_cvt_pk_bf16_f32 v134, v134, v135
	v_cvt_pk_bf16_f32 v135, v136, v137
	v_cvt_pk_bf16_f32 v136, v138, v139
	v_cvt_pk_bf16_f32 v137, v140, v141
	v_fma_f32 v143, -v36, v142, 1.0
	v_fma_f32 v142, v143, v142, v142
	v_mov_b32_e32 v143, v142
	ds_read_b64 v[82:83], v73 offset:53824
	ds_read_b64 v[84:85], v73 offset:53856
	s_waitcnt lgkmcnt(12)
	v_mfma_f32_16x16x32_bf16 v[32:35], v[48:51], v[78:81], 0
	ds_read_b64 v[90:91], v73 offset:62272
	ds_read_b64 v[92:93], v73 offset:62304
	s_waitcnt lgkmcnt(12)
	v_mfma_f32_16x16x32_bf16 v[36:39], v[52:55], v[78:81], 0
	ds_read_b64 v[48:49], v73 offset:36992
	ds_read_b64 v[50:51], v73 offset:37024
	s_waitcnt lgkmcnt(12)
	v_mfma_f32_16x16x32_bf16 v[40:43], v[56:59], v[78:81], 0
	ds_read_b64 v[52:53], v73 offset:45440
	ds_read_b64 v[54:55], v73 offset:45472
	s_waitcnt lgkmcnt(12)
	v_mfma_f32_16x16x32_bf16 v[44:47], v[60:63], v[78:81], 0
	ds_read_b64 v[56:57], v73 offset:53888
	ds_read_b64 v[58:59], v73 offset:53920
	s_waitcnt lgkmcnt(12)
	v_mfma_f32_16x16x32_bf16 v[32:35], v[64:67], v[86:89], v[32:35]
	ds_read_b64 v[60:61], v73 offset:62336
	ds_read_b64 v[62:63], v73 offset:62368
	s_waitcnt lgkmcnt(12)
	v_mfma_f32_16x16x32_bf16 v[36:39], v[68:71], v[86:89], v[36:39]
	ds_read_b64 v[64:65], v73 offset:37056
	ds_read_b64 v[66:67], v73 offset:37088
	s_waitcnt lgkmcnt(12)
	v_mfma_f32_16x16x32_bf16 v[40:43], v[82:85], v[86:89], v[40:43]
	ds_read_b64 v[68:69], v73 offset:45504
	ds_read_b64 v[70:71], v73 offset:45536
	s_waitcnt lgkmcnt(12)
	v_mfma_f32_16x16x32_bf16 v[44:47], v[90:93], v[86:89], v[44:47]
	ds_read_b64 v[82:83], v73 offset:53952
	ds_read_b64 v[84:85], v73 offset:53984
	s_waitcnt lgkmcnt(12)
	v_mfma_f32_16x16x32_bf16 v[32:35], v[48:51], v[94:97], v[32:35]
	ds_read_b64 v[90:91], v73 offset:62400
	ds_read_b64 v[92:93], v73 offset:62432
	s_waitcnt lgkmcnt(12)
	v_mfma_f32_16x16x32_bf16 v[36:39], v[52:55], v[94:97], v[36:39]
	ds_read_b64 v[48:49], v73 offset:37120
	ds_read_b64 v[50:51], v73 offset:37152
	s_waitcnt lgkmcnt(12)
	v_mfma_f32_16x16x32_bf16 v[40:43], v[56:59], v[94:97], v[40:43]
	ds_read_b64 v[52:53], v73 offset:45568
	ds_read_b64 v[54:55], v73 offset:45600
	s_waitcnt lgkmcnt(12)
	v_mfma_f32_16x16x32_bf16 v[44:47], v[60:63], v[94:97], v[44:47]
	ds_read_b64 v[56:57], v73 offset:54016
	ds_read_b64 v[58:59], v73 offset:54048
	s_waitcnt lgkmcnt(12)
	v_mfma_f32_16x16x32_bf16 v[32:35], v[64:67], v[102:105], v[32:35]
	ds_read_b64 v[60:61], v73 offset:62464
	ds_read_b64 v[62:63], v73 offset:62496
	s_waitcnt lgkmcnt(12)
	v_mfma_f32_16x16x32_bf16 v[36:39], v[68:71], v[102:105], v[36:39]
	ds_read_b64 v[64:65], v73 offset:37184
	ds_read_b64 v[66:67], v73 offset:37216
	s_waitcnt lgkmcnt(12)
	v_mfma_f32_16x16x32_bf16 v[40:43], v[82:85], v[102:105], v[40:43]
	ds_read_b64 v[68:69], v73 offset:45632
	ds_read_b64 v[70:71], v73 offset:45664
	s_waitcnt lgkmcnt(12)
	v_mfma_f32_16x16x32_bf16 v[44:47], v[90:93], v[102:105], v[44:47]
	ds_read_b64 v[82:83], v73 offset:54080
	ds_read_b64 v[84:85], v73 offset:54112
	s_waitcnt lgkmcnt(12)
	v_mfma_f32_16x16x32_bf16 v[32:35], v[48:51], v[110:113], v[32:35]
	ds_read_b64 v[90:91], v73 offset:62528
	ds_read_b64 v[92:93], v73 offset:62560
	s_waitcnt lgkmcnt(12)
	v_mfma_f32_16x16x32_bf16 v[36:39], v[52:55], v[110:113], v[36:39]
	ds_read_b64 v[48:49], v73 offset:37248
	ds_read_b64 v[50:51], v73 offset:37280
	s_waitcnt lgkmcnt(12)
	v_mfma_f32_16x16x32_bf16 v[40:43], v[56:59], v[110:113], v[40:43]
	ds_read_b64 v[52:53], v73 offset:45696
	ds_read_b64 v[54:55], v73 offset:45728
	s_waitcnt lgkmcnt(12)
	v_mfma_f32_16x16x32_bf16 v[44:47], v[60:63], v[110:113], v[44:47]
	ds_read_b64 v[56:57], v73 offset:54144
	ds_read_b64 v[58:59], v73 offset:54176
	s_waitcnt lgkmcnt(12)
	v_mfma_f32_16x16x32_bf16 v[32:35], v[64:67], v[118:121], v[32:35]
	ds_read_b64 v[60:61], v73 offset:62592
	ds_read_b64 v[62:63], v73 offset:62624
	s_waitcnt lgkmcnt(12)
	v_mfma_f32_16x16x32_bf16 v[36:39], v[68:71], v[118:121], v[36:39]
	ds_read_b64 v[64:65], v73 offset:37312
	ds_read_b64 v[66:67], v73 offset:37344
	s_waitcnt lgkmcnt(12)
	v_mfma_f32_16x16x32_bf16 v[40:43], v[82:85], v[118:121], v[40:43]
	ds_read_b64 v[68:69], v73 offset:45760
	ds_read_b64 v[70:71], v73 offset:45792
	s_waitcnt lgkmcnt(12)
	v_mfma_f32_16x16x32_bf16 v[44:47], v[90:93], v[118:121], v[44:47]
	ds_read_b64 v[82:83], v73 offset:54208
	ds_read_b64 v[84:85], v73 offset:54240
	s_waitcnt lgkmcnt(12)
	v_mfma_f32_16x16x32_bf16 v[32:35], v[48:51], v[126:129], v[32:35]
	ds_read_b64 v[90:91], v73 offset:62656
	ds_read_b64 v[92:93], v73 offset:62688
	s_waitcnt lgkmcnt(12)
	v_mfma_f32_16x16x32_bf16 v[36:39], v[52:55], v[126:129], v[36:39]
	s_waitcnt lgkmcnt(10)
	v_mfma_f32_16x16x32_bf16 v[40:43], v[56:59], v[126:129], v[40:43]
	s_waitcnt lgkmcnt(8)
	v_mfma_f32_16x16x32_bf16 v[44:47], v[60:63], v[126:129], v[44:47]
	s_waitcnt lgkmcnt(6)
	v_mfma_f32_16x16x32_bf16 v[32:35], v[64:67], v[134:137], v[32:35]
	s_waitcnt lgkmcnt(4)
	v_mfma_f32_16x16x32_bf16 v[36:39], v[68:71], v[134:137], v[36:39]
	s_waitcnt lgkmcnt(2)
	v_mfma_f32_16x16x32_bf16 v[40:43], v[82:85], v[134:137], v[40:43]
	s_waitcnt lgkmcnt(0)
	v_mfma_f32_16x16x32_bf16 v[44:47], v[90:93], v[134:137], v[44:47]
	ds_read_b128 v[48:51], v72 offset:0
	ds_read_b128 v[52:55], v146 offset:0
	ds_read_b128 v[56:59], v72 offset:2048
	ds_read_b128 v[60:63], v146 offset:2048
	ds_read_b128 v[64:67], v72 offset:4096
	ds_read_b128 v[68:71], v146 offset:4096
	s_add_u32 s16, s12, 0x8000
	s_addc_u32 s17, s13, 0
	s_nop 7
	v_pk_mul_f32 v[32:33], v[32:33], v[142:143]
	v_pk_mul_f32 v[34:35], v[34:35], v[142:143]
	v_pk_mul_f32 v[36:37], v[36:37], v[142:143]
	v_pk_mul_f32 v[38:39], v[38:39], v[142:143]
	v_pk_mul_f32 v[40:41], v[40:41], v[142:143]
	v_pk_mul_f32 v[42:43], v[42:43], v[142:143]
	v_pk_mul_f32 v[44:45], v[44:45], v[142:143]
	v_pk_mul_f32 v[46:47], v[46:47], v[142:143]
	v_cvt_pk_bf16_f32 v32, v32, v33
	v_cvt_pk_bf16_f32 v33, v34, v35
	v_cvt_pk_bf16_f32 v36, v36, v37
	v_cvt_pk_bf16_f32 v37, v38, v39
	v_cvt_pk_bf16_f32 v40, v40, v41
	v_cvt_pk_bf16_f32 v41, v42, v43
	v_cvt_pk_bf16_f32 v44, v44, v45
	v_cvt_pk_bf16_f32 v45, v46, v47
	global_store_dwordx2 v74, v[32:33], s[16:17] offset:0
	global_store_dwordx2 v74, v[36:37], s[16:17] offset:32
	global_store_dwordx2 v74, v[40:41], s[16:17] offset:64
	global_store_dwordx2 v74, v[44:45], s[16:17] offset:96
	ds_read_b128 v[32:35], v72 offset:6144
	ds_read_b128 v[36:39], v146 offset:6144
	ds_read_b128 v[40:43], v72 offset:8192
	s_waitcnt lgkmcnt(8)
	v_mfma_f32_16x16x32_bf16 v[78:81], v[48:51], v[16:19], 0
	ds_read_b128 v[44:47], v146 offset:8192
	s_waitcnt lgkmcnt(8)
	v_mfma_f32_16x16x32_bf16 v[78:81], v[52:55], v[20:23], v[78:81]
	ds_read_b128 v[48:51], v72 offset:10240
	s_waitcnt lgkmcnt(8)
	v_mfma_f32_16x16x32_bf16 v[82:85], v[56:59], v[16:19], 0
	ds_read_b128 v[52:55], v146 offset:10240
	s_waitcnt lgkmcnt(8)
	v_mfma_f32_16x16x32_bf16 v[82:85], v[60:63], v[20:23], v[82:85]
	ds_read_b128 v[56:59], v72 offset:12288
	s_waitcnt lgkmcnt(8)
	v_mfma_f32_16x16x32_bf16 v[86:89], v[64:67], v[16:19], 0
	ds_read_b128 v[60:63], v146 offset:12288
	s_waitcnt lgkmcnt(8)
	v_mfma_f32_16x16x32_bf16 v[86:89], v[68:71], v[20:23], v[86:89]
	ds_read_b128 v[64:67], v72 offset:14336
	s_waitcnt lgkmcnt(8)
	v_mfma_f32_16x16x32_bf16 v[90:93], v[32:35], v[16:19], 0
	ds_read_b128 v[68:71], v146 offset:14336
	s_waitcnt lgkmcnt(8)
	v_mfma_f32_16x16x32_bf16 v[90:93], v[36:39], v[20:23], v[90:93]
	ds_read_b128 v[32:35], v72 offset:16384
	s_waitcnt lgkmcnt(8)
	v_mfma_f32_16x16x32_bf16 v[94:97], v[40:43], v[16:19], 0
	ds_read_b128 v[36:39], v146 offset:16384
	s_waitcnt lgkmcnt(8)
	v_mfma_f32_16x16x32_bf16 v[94:97], v[44:47], v[20:23], v[94:97]
	ds_read_b128 v[40:43], v72 offset:18432
	s_waitcnt lgkmcnt(8)
	v_mfma_f32_16x16x32_bf16 v[98:101], v[48:51], v[16:19], 0
	ds_read_b128 v[44:47], v146 offset:18432
	s_waitcnt lgkmcnt(8)
	v_mfma_f32_16x16x32_bf16 v[98:101], v[52:55], v[20:23], v[98:101]
	ds_read_b128 v[48:51], v72 offset:20480
	s_waitcnt lgkmcnt(8)
	v_mfma_f32_16x16x32_bf16 v[102:105], v[56:59], v[16:19], 0
	ds_read_b128 v[52:55], v146 offset:20480
	s_waitcnt lgkmcnt(8)
	v_mfma_f32_16x16x32_bf16 v[102:105], v[60:63], v[20:23], v[102:105]
	ds_read_b128 v[56:59], v72 offset:22528
	s_waitcnt lgkmcnt(8)
	v_mfma_f32_16x16x32_bf16 v[106:109], v[64:67], v[16:19], 0
	ds_read_b128 v[60:63], v146 offset:22528
	s_waitcnt lgkmcnt(8)
	v_mfma_f32_16x16x32_bf16 v[106:109], v[68:71], v[20:23], v[106:109]
	ds_read_b128 v[64:67], v72 offset:24576
	s_waitcnt lgkmcnt(8)
	v_mfma_f32_16x16x32_bf16 v[110:113], v[32:35], v[16:19], 0
	ds_read_b128 v[68:71], v146 offset:24576
	s_waitcnt lgkmcnt(8)
	v_mfma_f32_16x16x32_bf16 v[110:113], v[36:39], v[20:23], v[110:113]
	ds_read_b128 v[32:35], v72 offset:26624
	s_waitcnt lgkmcnt(8)
	v_mfma_f32_16x16x32_bf16 v[114:117], v[40:43], v[16:19], 0
	ds_read_b128 v[36:39], v146 offset:26624
	s_waitcnt lgkmcnt(8)
	v_mfma_f32_16x16x32_bf16 v[114:117], v[44:47], v[20:23], v[114:117]
	ds_read_b128 v[40:43], v72 offset:28672
	s_waitcnt lgkmcnt(8)
	v_mfma_f32_16x16x32_bf16 v[118:121], v[48:51], v[16:19], 0
	ds_read_b128 v[44:47], v146 offset:28672
	s_waitcnt lgkmcnt(8)
	v_mfma_f32_16x16x32_bf16 v[118:121], v[52:55], v[20:23], v[118:121]
	ds_read_b128 v[48:51], v72 offset:30720
	s_waitcnt lgkmcnt(8)
	v_mfma_f32_16x16x32_bf16 v[122:125], v[56:59], v[16:19], 0
	ds_read_b128 v[52:55], v146 offset:30720
	s_waitcnt lgkmcnt(8)
	v_mfma_f32_16x16x32_bf16 v[122:125], v[60:63], v[20:23], v[122:125]
	s_waitcnt lgkmcnt(7)
	v_mfma_f32_16x16x32_bf16 v[126:129], v[64:67], v[16:19], 0
	s_waitcnt lgkmcnt(6)
	v_mfma_f32_16x16x32_bf16 v[126:129], v[68:71], v[20:23], v[126:129]
	s_waitcnt lgkmcnt(5)
	v_mfma_f32_16x16x32_bf16 v[130:133], v[32:35], v[16:19], 0
	s_waitcnt lgkmcnt(4)
	v_mfma_f32_16x16x32_bf16 v[130:133], v[36:39], v[20:23], v[130:133]
	s_waitcnt lgkmcnt(3)
	v_mfma_f32_16x16x32_bf16 v[134:137], v[40:43], v[16:19], 0
	s_waitcnt lgkmcnt(2)
	v_mfma_f32_16x16x32_bf16 v[134:137], v[44:47], v[20:23], v[134:137]
	s_waitcnt lgkmcnt(1)
	v_mfma_f32_16x16x32_bf16 v[138:141], v[48:51], v[16:19], 0
	s_waitcnt lgkmcnt(0)
	v_mfma_f32_16x16x32_bf16 v[138:141], v[52:55], v[20:23], v[138:141]
	ds_read_b64 v[48:49], v73 offset:36864
	ds_read_b64 v[50:51], v73 offset:36896
	ds_read_b64 v[52:53], v73 offset:45312
	ds_read_b64 v[54:55], v73 offset:45344
	ds_read_b64 v[56:57], v73 offset:53760
	ds_read_b64 v[58:59], v73 offset:53792
	ds_read_b64 v[60:61], v73 offset:62208
	ds_read_b64 v[62:63], v73 offset:62240
	ds_read_b64 v[64:65], v73 offset:36928
	ds_read_b64 v[66:67], v73 offset:36960
	ds_read_b64 v[68:69], v73 offset:45376
	ds_read_b64 v[70:71], v73 offset:45408
	v_max3_f32 v36, v78, v79, v80
	v_max3_f32 v36, v36, v81, v82
	v_max3_f32 v36, v36, v83, v84
	v_max3_f32 v36, v36, v85, v86
	v_max3_f32 v36, v36, v87, v88
	v_max3_f32 v36, v36, v89, v90
	v_max3_f32 v36, v36, v91, v92
	v_max3_f32 v36, v36, v93, v94
	v_max3_f32 v36, v36, v95, v96
	v_max3_f32 v36, v36, v97, v98
	v_max3_f32 v36, v36, v99, v100
	v_max3_f32 v36, v36, v101, v102
	v_max3_f32 v36, v36, v103, v104
	v_max3_f32 v36, v36, v105, v106
	v_max3_f32 v36, v36, v107, v108
	v_max3_f32 v36, v36, v109, v110
	v_max3_f32 v36, v36, v111, v112
	v_max3_f32 v36, v36, v113, v114
	v_max3_f32 v36, v36, v115, v116
	v_max3_f32 v36, v36, v117, v118
	v_max3_f32 v36, v36, v119, v120
	v_max3_f32 v36, v36, v121, v122
	v_max3_f32 v36, v36, v123, v124
	v_max3_f32 v36, v36, v125, v126
	v_max3_f32 v36, v36, v127, v128
	v_max3_f32 v36, v36, v129, v130
	v_max3_f32 v36, v36, v131, v132
	v_max3_f32 v36, v36, v133, v134
	v_max3_f32 v36, v36, v135, v136
	v_max3_f32 v36, v36, v137, v138
	v_max3_f32 v36, v36, v139, v140
	v_max_f32_e32 v36, v36, v141
	v_mov_b32_e32 v37, v36
	s_nop 1
	v_permlane16_swap_b32_e32 v36, v37
	v_max_f32_e32 v36, v36, v37
	v_mov_b32_e32 v37, v36
	s_nop 1
	v_permlane32_swap_b32_e32 v36, v37
	v_max_f32_e32 v36, v36, v37
	v_mul_f32_e64 v38, v36, -v144
	v_mov_b32_e32 v40, 0
	v_mov_b32_e32 v41, 0
	v_mov_b32_e32 v39, v38
	v_pk_fma_f32 v[78:79], v[78:79], v[144:145], v[38:39]
	v_pk_fma_f32 v[80:81], v[80:81], v[144:145], v[38:39]
	v_exp_f32_e32 v78, v78
	v_exp_f32_e32 v79, v79
	v_exp_f32_e32 v80, v80
	v_exp_f32_e32 v81, v81
	v_pk_fma_f32 v[82:83], v[82:83], v[144:145], v[38:39]
	v_pk_fma_f32 v[84:85], v[84:85], v[144:145], v[38:39]
	v_exp_f32_e32 v82, v82
	v_exp_f32_e32 v83, v83
	v_exp_f32_e32 v84, v84
	v_exp_f32_e32 v85, v85
	v_pk_add_f32 v[40:41], v[40:41], v[78:79]
	v_pk_add_f32 v[40:41], v[40:41], v[80:81]
	v_pk_fma_f32 v[86:87], v[86:87], v[144:145], v[38:39]
	v_pk_fma_f32 v[88:89], v[88:89], v[144:145], v[38:39]
	v_exp_f32_e32 v86, v86
	v_exp_f32_e32 v87, v87
	v_exp_f32_e32 v88, v88
	v_exp_f32_e32 v89, v89
	v_pk_add_f32 v[40:41], v[40:41], v[82:83]
	v_pk_add_f32 v[40:41], v[40:41], v[84:85]
	v_pk_fma_f32 v[90:91], v[90:91], v[144:145], v[38:39]
	v_pk_fma_f32 v[92:93], v[92:93], v[144:145], v[38:39]
	v_exp_f32_e32 v90, v90
	v_exp_f32_e32 v91, v91
	v_exp_f32_e32 v92, v92
	v_exp_f32_e32 v93, v93
	v_pk_add_f32 v[40:41], v[40:41], v[86:87]
	v_pk_add_f32 v[40:41], v[40:41], v[88:89]
	v_pk_fma_f32 v[94:95], v[94:95], v[144:145], v[38:39]
	v_pk_fma_f32 v[96:97], v[96:97], v[144:145], v[38:39]
	v_exp_f32_e32 v94, v94
	v_exp_f32_e32 v95, v95
	v_exp_f32_e32 v96, v96
	v_exp_f32_e32 v97, v97
	v_pk_add_f32 v[40:41], v[40:41], v[90:91]
	v_pk_add_f32 v[40:41], v[40:41], v[92:93]
	v_pk_fma_f32 v[98:99], v[98:99], v[144:145], v[38:39]
	v_pk_fma_f32 v[100:101], v[100:101], v[144:145], v[38:39]
	v_exp_f32_e32 v98, v98
	v_exp_f32_e32 v99, v99
	v_exp_f32_e32 v100, v100
	v_exp_f32_e32 v101, v101
	v_pk_add_f32 v[40:41], v[40:41], v[94:95]
	v_pk_add_f32 v[40:41], v[40:41], v[96:97]
	v_pk_fma_f32 v[102:103], v[102:103], v[144:145], v[38:39]
	v_pk_fma_f32 v[104:105], v[104:105], v[144:145], v[38:39]
	v_exp_f32_e32 v102, v102
	v_exp_f32_e32 v103, v103
	v_exp_f32_e32 v104, v104
	v_exp_f32_e32 v105, v105
	v_pk_add_f32 v[40:41], v[40:41], v[98:99]
	v_pk_add_f32 v[40:41], v[40:41], v[100:101]
	v_pk_fma_f32 v[106:107], v[106:107], v[144:145], v[38:39]
	v_pk_fma_f32 v[108:109], v[108:109], v[144:145], v[38:39]
	v_exp_f32_e32 v106, v106
	v_exp_f32_e32 v107, v107
	v_exp_f32_e32 v108, v108
	v_exp_f32_e32 v109, v109
	v_pk_add_f32 v[40:41], v[40:41], v[102:103]
	v_pk_add_f32 v[40:41], v[40:41], v[104:105]
	v_pk_fma_f32 v[110:111], v[110:111], v[144:145], v[38:39]
	v_pk_fma_f32 v[112:113], v[112:113], v[144:145], v[38:39]
	v_exp_f32_e32 v110, v110
	v_exp_f32_e32 v111, v111
	v_exp_f32_e32 v112, v112
	v_exp_f32_e32 v113, v113
	v_pk_add_f32 v[40:41], v[40:41], v[106:107]
	v_pk_add_f32 v[40:41], v[40:41], v[108:109]
	v_pk_fma_f32 v[114:115], v[114:115], v[144:145], v[38:39]
	v_pk_fma_f32 v[116:117], v[116:117], v[144:145], v[38:39]
	v_exp_f32_e32 v114, v114
	v_exp_f32_e32 v115, v115
	v_exp_f32_e32 v116, v116
	v_exp_f32_e32 v117, v117
	v_pk_add_f32 v[40:41], v[40:41], v[110:111]
	v_pk_add_f32 v[40:41], v[40:41], v[112:113]
	v_pk_fma_f32 v[118:119], v[118:119], v[144:145], v[38:39]
	v_pk_fma_f32 v[120:121], v[120:121], v[144:145], v[38:39]
	v_exp_f32_e32 v118, v118
	v_exp_f32_e32 v119, v119
	v_exp_f32_e32 v120, v120
	v_exp_f32_e32 v121, v121
	v_pk_add_f32 v[40:41], v[40:41], v[114:115]
	v_pk_add_f32 v[40:41], v[40:41], v[116:117]
	v_pk_fma_f32 v[122:123], v[122:123], v[144:145], v[38:39]
	v_pk_fma_f32 v[124:125], v[124:125], v[144:145], v[38:39]
	v_exp_f32_e32 v122, v122
	v_exp_f32_e32 v123, v123
	v_exp_f32_e32 v124, v124
	v_exp_f32_e32 v125, v125
	v_pk_add_f32 v[40:41], v[40:41], v[118:119]
	v_pk_add_f32 v[40:41], v[40:41], v[120:121]
	v_pk_fma_f32 v[126:127], v[126:127], v[144:145], v[38:39]
	v_pk_fma_f32 v[128:129], v[128:129], v[144:145], v[38:39]
	v_exp_f32_e32 v126, v126
	v_exp_f32_e32 v127, v127
	v_exp_f32_e32 v128, v128
	v_exp_f32_e32 v129, v129
	v_pk_add_f32 v[40:41], v[40:41], v[122:123]
	v_pk_add_f32 v[40:41], v[40:41], v[124:125]
	v_pk_fma_f32 v[130:131], v[130:131], v[144:145], v[38:39]
	v_pk_fma_f32 v[132:133], v[132:133], v[144:145], v[38:39]
	v_exp_f32_e32 v130, v130
	v_exp_f32_e32 v131, v131
	v_exp_f32_e32 v132, v132
	v_exp_f32_e32 v133, v133
	v_pk_add_f32 v[40:41], v[40:41], v[126:127]
	v_pk_add_f32 v[40:41], v[40:41], v[128:129]
	v_pk_fma_f32 v[134:135], v[134:135], v[144:145], v[38:39]
	v_pk_fma_f32 v[136:137], v[136:137], v[144:145], v[38:39]
	v_exp_f32_e32 v134, v134
	v_exp_f32_e32 v135, v135
	v_exp_f32_e32 v136, v136
	v_exp_f32_e32 v137, v137
	v_pk_add_f32 v[40:41], v[40:41], v[130:131]
	v_pk_add_f32 v[40:41], v[40:41], v[132:133]
	v_pk_fma_f32 v[138:139], v[138:139], v[144:145], v[38:39]
	v_pk_fma_f32 v[140:141], v[140:141], v[144:145], v[38:39]
	v_exp_f32_e32 v138, v138
	v_exp_f32_e32 v139, v139
	v_exp_f32_e32 v140, v140
	v_exp_f32_e32 v141, v141
	v_pk_add_f32 v[40:41], v[40:41], v[134:135]
	v_pk_add_f32 v[40:41], v[40:41], v[136:137]
	s_nop 0
	v_pk_add_f32 v[40:41], v[40:41], v[138:139]
	v_pk_add_f32 v[40:41], v[40:41], v[140:141]
	v_add_f32_e32 v36, v40, v41
	v_mov_b32_e32 v37, v36
	s_nop 1
	v_permlane16_swap_b32_e32 v36, v37
	v_add_f32_e32 v36, v36, v37
	v_mov_b32_e32 v37, v36
	s_nop 1
	v_permlane32_swap_b32_e32 v36, v37
	v_add_f32_e32 v36, v36, v37
	v_rcp_f32_e32 v142, v36
	v_cvt_pk_bf16_f32 v78, v78, v79
	v_cvt_pk_bf16_f32 v79, v80, v81
	v_cvt_pk_bf16_f32 v80, v82, v83
	v_cvt_pk_bf16_f32 v81, v84, v85
	v_cvt_pk_bf16_f32 v86, v86, v87
	v_cvt_pk_bf16_f32 v87, v88, v89
	v_cvt_pk_bf16_f32 v88, v90, v91
	v_cvt_pk_bf16_f32 v89, v92, v93
	v_cvt_pk_bf16_f32 v94, v94, v95
	v_cvt_pk_bf16_f32 v95, v96, v97
	v_cvt_pk_bf16_f32 v96, v98, v99
	v_cvt_pk_bf16_f32 v97, v100, v101
	v_cvt_pk_bf16_f32 v102, v102, v103
	v_cvt_pk_bf16_f32 v103, v104, v105
	v_cvt_pk_bf16_f32 v104, v106, v107
	v_cvt_pk_bf16_f32 v105, v108, v109
	v_cvt_pk_bf16_f32 v110, v110, v111
	v_cvt_pk_bf16_f32 v111, v112, v113
	v_cvt_pk_bf16_f32 v112, v114, v115
	v_cvt_pk_bf16_f32 v113, v116, v117
	v_cvt_pk_bf16_f32 v118, v118, v119
	v_cvt_pk_bf16_f32 v119, v120, v121
	v_cvt_pk_bf16_f32 v120, v122, v123
	v_cvt_pk_bf16_f32 v121, v124, v125
	v_cvt_pk_bf16_f32 v126, v126, v127
	v_cvt_pk_bf16_f32 v127, v128, v129
	v_cvt_pk_bf16_f32 v128, v130, v131
	v_cvt_pk_bf16_f32 v129, v132, v133
	v_cvt_pk_bf16_f32 v134, v134, v135
	v_cvt_pk_bf16_f32 v135, v136, v137
	v_cvt_pk_bf16_f32 v136, v138, v139
	v_cvt_pk_bf16_f32 v137, v140, v141
	v_fma_f32 v143, -v36, v142, 1.0
	v_fma_f32 v142, v143, v142, v142
	v_mov_b32_e32 v143, v142
	ds_read_b64 v[82:83], v73 offset:53824
	ds_read_b64 v[84:85], v73 offset:53856
	s_waitcnt lgkmcnt(12)
	v_mfma_f32_16x16x32_bf16 v[32:35], v[48:51], v[78:81], 0
	ds_read_b64 v[90:91], v73 offset:62272
	ds_read_b64 v[92:93], v73 offset:62304
	s_waitcnt lgkmcnt(12)
	v_mfma_f32_16x16x32_bf16 v[36:39], v[52:55], v[78:81], 0
	ds_read_b64 v[48:49], v73 offset:36992
	ds_read_b64 v[50:51], v73 offset:37024
	s_waitcnt lgkmcnt(12)
	v_mfma_f32_16x16x32_bf16 v[40:43], v[56:59], v[78:81], 0
	ds_read_b64 v[52:53], v73 offset:45440
	ds_read_b64 v[54:55], v73 offset:45472
	s_waitcnt lgkmcnt(12)
	v_mfma_f32_16x16x32_bf16 v[44:47], v[60:63], v[78:81], 0
	ds_read_b64 v[56:57], v73 offset:53888
	ds_read_b64 v[58:59], v73 offset:53920
	s_waitcnt lgkmcnt(12)
	v_mfma_f32_16x16x32_bf16 v[32:35], v[64:67], v[86:89], v[32:35]
	ds_read_b64 v[60:61], v73 offset:62336
	ds_read_b64 v[62:63], v73 offset:62368
	s_waitcnt lgkmcnt(12)
	v_mfma_f32_16x16x32_bf16 v[36:39], v[68:71], v[86:89], v[36:39]
	ds_read_b64 v[64:65], v73 offset:37056
	ds_read_b64 v[66:67], v73 offset:37088
	s_waitcnt lgkmcnt(12)
	v_mfma_f32_16x16x32_bf16 v[40:43], v[82:85], v[86:89], v[40:43]
	ds_read_b64 v[68:69], v73 offset:45504
	ds_read_b64 v[70:71], v73 offset:45536
	s_waitcnt lgkmcnt(12)
	v_mfma_f32_16x16x32_bf16 v[44:47], v[90:93], v[86:89], v[44:47]
	ds_read_b64 v[82:83], v73 offset:53952
	ds_read_b64 v[84:85], v73 offset:53984
	s_waitcnt lgkmcnt(12)
	v_mfma_f32_16x16x32_bf16 v[32:35], v[48:51], v[94:97], v[32:35]
	ds_read_b64 v[90:91], v73 offset:62400
	ds_read_b64 v[92:93], v73 offset:62432
	s_waitcnt lgkmcnt(12)
	v_mfma_f32_16x16x32_bf16 v[36:39], v[52:55], v[94:97], v[36:39]
	ds_read_b64 v[48:49], v73 offset:37120
	ds_read_b64 v[50:51], v73 offset:37152
	s_waitcnt lgkmcnt(12)
	v_mfma_f32_16x16x32_bf16 v[40:43], v[56:59], v[94:97], v[40:43]
	ds_read_b64 v[52:53], v73 offset:45568
	ds_read_b64 v[54:55], v73 offset:45600
	s_waitcnt lgkmcnt(12)
	v_mfma_f32_16x16x32_bf16 v[44:47], v[60:63], v[94:97], v[44:47]
	ds_read_b64 v[56:57], v73 offset:54016
	ds_read_b64 v[58:59], v73 offset:54048
	s_waitcnt lgkmcnt(12)
	v_mfma_f32_16x16x32_bf16 v[32:35], v[64:67], v[102:105], v[32:35]
	ds_read_b64 v[60:61], v73 offset:62464
	ds_read_b64 v[62:63], v73 offset:62496
	s_waitcnt lgkmcnt(12)
	v_mfma_f32_16x16x32_bf16 v[36:39], v[68:71], v[102:105], v[36:39]
	ds_read_b64 v[64:65], v73 offset:37184
	ds_read_b64 v[66:67], v73 offset:37216
	s_waitcnt lgkmcnt(12)
	v_mfma_f32_16x16x32_bf16 v[40:43], v[82:85], v[102:105], v[40:43]
	ds_read_b64 v[68:69], v73 offset:45632
	ds_read_b64 v[70:71], v73 offset:45664
	s_waitcnt lgkmcnt(12)
	v_mfma_f32_16x16x32_bf16 v[44:47], v[90:93], v[102:105], v[44:47]
	ds_read_b64 v[82:83], v73 offset:54080
	ds_read_b64 v[84:85], v73 offset:54112
	s_waitcnt lgkmcnt(12)
	v_mfma_f32_16x16x32_bf16 v[32:35], v[48:51], v[110:113], v[32:35]
	ds_read_b64 v[90:91], v73 offset:62528
	ds_read_b64 v[92:93], v73 offset:62560
	s_waitcnt lgkmcnt(12)
	v_mfma_f32_16x16x32_bf16 v[36:39], v[52:55], v[110:113], v[36:39]
	ds_read_b64 v[48:49], v73 offset:37248
	ds_read_b64 v[50:51], v73 offset:37280
	s_waitcnt lgkmcnt(12)
	v_mfma_f32_16x16x32_bf16 v[40:43], v[56:59], v[110:113], v[40:43]
	ds_read_b64 v[52:53], v73 offset:45696
	ds_read_b64 v[54:55], v73 offset:45728
	s_waitcnt lgkmcnt(12)
	v_mfma_f32_16x16x32_bf16 v[44:47], v[60:63], v[110:113], v[44:47]
	ds_read_b64 v[56:57], v73 offset:54144
	ds_read_b64 v[58:59], v73 offset:54176
	s_waitcnt lgkmcnt(12)
	v_mfma_f32_16x16x32_bf16 v[32:35], v[64:67], v[118:121], v[32:35]
	ds_read_b64 v[60:61], v73 offset:62592
	ds_read_b64 v[62:63], v73 offset:62624
	s_waitcnt lgkmcnt(12)
	v_mfma_f32_16x16x32_bf16 v[36:39], v[68:71], v[118:121], v[36:39]
	ds_read_b64 v[64:65], v73 offset:37312
	ds_read_b64 v[66:67], v73 offset:37344
	s_waitcnt lgkmcnt(12)
	v_mfma_f32_16x16x32_bf16 v[40:43], v[82:85], v[118:121], v[40:43]
	ds_read_b64 v[68:69], v73 offset:45760
	ds_read_b64 v[70:71], v73 offset:45792
	s_waitcnt lgkmcnt(12)
	v_mfma_f32_16x16x32_bf16 v[44:47], v[90:93], v[118:121], v[44:47]
	ds_read_b64 v[82:83], v73 offset:54208
	ds_read_b64 v[84:85], v73 offset:54240
	s_waitcnt lgkmcnt(12)
	v_mfma_f32_16x16x32_bf16 v[32:35], v[48:51], v[126:129], v[32:35]
	ds_read_b64 v[90:91], v73 offset:62656
	ds_read_b64 v[92:93], v73 offset:62688
	s_waitcnt lgkmcnt(12)
	v_mfma_f32_16x16x32_bf16 v[36:39], v[52:55], v[126:129], v[36:39]
	s_waitcnt lgkmcnt(10)
	v_mfma_f32_16x16x32_bf16 v[40:43], v[56:59], v[126:129], v[40:43]
	s_waitcnt lgkmcnt(8)
	v_mfma_f32_16x16x32_bf16 v[44:47], v[60:63], v[126:129], v[44:47]
	s_waitcnt lgkmcnt(6)
	v_mfma_f32_16x16x32_bf16 v[32:35], v[64:67], v[134:137], v[32:35]
	s_waitcnt lgkmcnt(4)
	v_mfma_f32_16x16x32_bf16 v[36:39], v[68:71], v[134:137], v[36:39]
	s_waitcnt lgkmcnt(2)
	v_mfma_f32_16x16x32_bf16 v[40:43], v[82:85], v[134:137], v[40:43]
	s_waitcnt lgkmcnt(0)
	v_mfma_f32_16x16x32_bf16 v[44:47], v[90:93], v[134:137], v[44:47]
	ds_read_b128 v[48:51], v72 offset:0
	ds_read_b128 v[52:55], v146 offset:0
	ds_read_b128 v[56:59], v72 offset:2048
	ds_read_b128 v[60:63], v146 offset:2048
	ds_read_b128 v[64:67], v72 offset:4096
	ds_read_b128 v[68:71], v146 offset:4096
	s_add_u32 s16, s12, 0x80000
	s_addc_u32 s17, s13, 0
	s_nop 7
	v_pk_mul_f32 v[32:33], v[32:33], v[142:143]
	v_pk_mul_f32 v[34:35], v[34:35], v[142:143]
	v_pk_mul_f32 v[36:37], v[36:37], v[142:143]
	v_pk_mul_f32 v[38:39], v[38:39], v[142:143]
	v_pk_mul_f32 v[40:41], v[40:41], v[142:143]
	v_pk_mul_f32 v[42:43], v[42:43], v[142:143]
	v_pk_mul_f32 v[44:45], v[44:45], v[142:143]
	v_pk_mul_f32 v[46:47], v[46:47], v[142:143]
	v_cvt_pk_bf16_f32 v32, v32, v33
	v_cvt_pk_bf16_f32 v33, v34, v35
	v_cvt_pk_bf16_f32 v36, v36, v37
	v_cvt_pk_bf16_f32 v37, v38, v39
	v_cvt_pk_bf16_f32 v40, v40, v41
	v_cvt_pk_bf16_f32 v41, v42, v43
	v_cvt_pk_bf16_f32 v44, v44, v45
	v_cvt_pk_bf16_f32 v45, v46, v47
	global_store_dwordx2 v74, v[32:33], s[16:17] offset:0
	global_store_dwordx2 v74, v[36:37], s[16:17] offset:32
	global_store_dwordx2 v74, v[40:41], s[16:17] offset:64
	global_store_dwordx2 v74, v[44:45], s[16:17] offset:96
	ds_read_b128 v[32:35], v72 offset:6144
	ds_read_b128 v[36:39], v146 offset:6144
	ds_read_b128 v[40:43], v72 offset:8192
	s_waitcnt lgkmcnt(8)
	v_mfma_f32_16x16x32_bf16 v[78:81], v[48:51], v[24:27], 0
	ds_read_b128 v[44:47], v146 offset:8192
	s_waitcnt lgkmcnt(8)
	v_mfma_f32_16x16x32_bf16 v[78:81], v[52:55], v[28:31], v[78:81]
	ds_read_b128 v[48:51], v72 offset:10240
	s_waitcnt lgkmcnt(8)
	v_mfma_f32_16x16x32_bf16 v[82:85], v[56:59], v[24:27], 0
	ds_read_b128 v[52:55], v146 offset:10240
	s_waitcnt lgkmcnt(8)
	v_mfma_f32_16x16x32_bf16 v[82:85], v[60:63], v[28:31], v[82:85]
	ds_read_b128 v[56:59], v72 offset:12288
	s_waitcnt lgkmcnt(8)
	v_mfma_f32_16x16x32_bf16 v[86:89], v[64:67], v[24:27], 0
	ds_read_b128 v[60:63], v146 offset:12288
	s_waitcnt lgkmcnt(8)
	v_mfma_f32_16x16x32_bf16 v[86:89], v[68:71], v[28:31], v[86:89]
	ds_read_b128 v[64:67], v72 offset:14336
	s_waitcnt lgkmcnt(8)
	v_mfma_f32_16x16x32_bf16 v[90:93], v[32:35], v[24:27], 0
	ds_read_b128 v[68:71], v146 offset:14336
	s_waitcnt lgkmcnt(8)
	v_mfma_f32_16x16x32_bf16 v[90:93], v[36:39], v[28:31], v[90:93]
	ds_read_b128 v[32:35], v72 offset:16384
	s_waitcnt lgkmcnt(8)
	v_mfma_f32_16x16x32_bf16 v[94:97], v[40:43], v[24:27], 0
	ds_read_b128 v[36:39], v146 offset:16384
	s_waitcnt lgkmcnt(8)
	v_mfma_f32_16x16x32_bf16 v[94:97], v[44:47], v[28:31], v[94:97]
	ds_read_b128 v[40:43], v72 offset:18432
	s_waitcnt lgkmcnt(8)
	v_mfma_f32_16x16x32_bf16 v[98:101], v[48:51], v[24:27], 0
	ds_read_b128 v[44:47], v146 offset:18432
	s_waitcnt lgkmcnt(8)
	v_mfma_f32_16x16x32_bf16 v[98:101], v[52:55], v[28:31], v[98:101]
	ds_read_b128 v[48:51], v72 offset:20480
	s_waitcnt lgkmcnt(8)
	v_mfma_f32_16x16x32_bf16 v[102:105], v[56:59], v[24:27], 0
	ds_read_b128 v[52:55], v146 offset:20480
	s_waitcnt lgkmcnt(8)
	v_mfma_f32_16x16x32_bf16 v[102:105], v[60:63], v[28:31], v[102:105]
	ds_read_b128 v[56:59], v72 offset:22528
	s_waitcnt lgkmcnt(8)
	v_mfma_f32_16x16x32_bf16 v[106:109], v[64:67], v[24:27], 0
	ds_read_b128 v[60:63], v146 offset:22528
	s_waitcnt lgkmcnt(8)
	v_mfma_f32_16x16x32_bf16 v[106:109], v[68:71], v[28:31], v[106:109]
	ds_read_b128 v[64:67], v72 offset:24576
	s_waitcnt lgkmcnt(8)
	v_mfma_f32_16x16x32_bf16 v[110:113], v[32:35], v[24:27], 0
	ds_read_b128 v[68:71], v146 offset:24576
	s_waitcnt lgkmcnt(8)
	v_mfma_f32_16x16x32_bf16 v[110:113], v[36:39], v[28:31], v[110:113]
	ds_read_b128 v[32:35], v72 offset:26624
	s_waitcnt lgkmcnt(8)
	v_mfma_f32_16x16x32_bf16 v[114:117], v[40:43], v[24:27], 0
	ds_read_b128 v[36:39], v146 offset:26624
	s_waitcnt lgkmcnt(8)
	v_mfma_f32_16x16x32_bf16 v[114:117], v[44:47], v[28:31], v[114:117]
	ds_read_b128 v[40:43], v72 offset:28672
	s_waitcnt lgkmcnt(8)
	v_mfma_f32_16x16x32_bf16 v[118:121], v[48:51], v[24:27], 0
	ds_read_b128 v[44:47], v146 offset:28672
	s_waitcnt lgkmcnt(8)
	v_mfma_f32_16x16x32_bf16 v[118:121], v[52:55], v[28:31], v[118:121]
	ds_read_b128 v[48:51], v72 offset:30720
	s_waitcnt lgkmcnt(8)
	v_mfma_f32_16x16x32_bf16 v[122:125], v[56:59], v[24:27], 0
	ds_read_b128 v[52:55], v146 offset:30720
	s_waitcnt lgkmcnt(8)
	v_mfma_f32_16x16x32_bf16 v[122:125], v[60:63], v[28:31], v[122:125]
	s_waitcnt lgkmcnt(7)
	v_mfma_f32_16x16x32_bf16 v[126:129], v[64:67], v[24:27], 0
	s_waitcnt lgkmcnt(6)
	v_mfma_f32_16x16x32_bf16 v[126:129], v[68:71], v[28:31], v[126:129]
	s_waitcnt lgkmcnt(5)
	v_mfma_f32_16x16x32_bf16 v[130:133], v[32:35], v[24:27], 0
	s_waitcnt lgkmcnt(4)
	v_mfma_f32_16x16x32_bf16 v[130:133], v[36:39], v[28:31], v[130:133]
	s_waitcnt lgkmcnt(3)
	v_mfma_f32_16x16x32_bf16 v[134:137], v[40:43], v[24:27], 0
	s_waitcnt lgkmcnt(2)
	v_mfma_f32_16x16x32_bf16 v[134:137], v[44:47], v[28:31], v[134:137]
	s_waitcnt lgkmcnt(1)
	v_mfma_f32_16x16x32_bf16 v[138:141], v[48:51], v[24:27], 0
	s_waitcnt lgkmcnt(0)
	v_mfma_f32_16x16x32_bf16 v[138:141], v[52:55], v[28:31], v[138:141]
	ds_read_b64 v[48:49], v73 offset:36864
	ds_read_b64 v[50:51], v73 offset:36896
	ds_read_b64 v[52:53], v73 offset:45312
	ds_read_b64 v[54:55], v73 offset:45344
	ds_read_b64 v[56:57], v73 offset:53760
	ds_read_b64 v[58:59], v73 offset:53792
	ds_read_b64 v[60:61], v73 offset:62208
	ds_read_b64 v[62:63], v73 offset:62240
	ds_read_b64 v[64:65], v73 offset:36928
	ds_read_b64 v[66:67], v73 offset:36960
	ds_read_b64 v[68:69], v73 offset:45376
	ds_read_b64 v[70:71], v73 offset:45408
	v_max3_f32 v36, v78, v79, v80
	v_max3_f32 v36, v36, v81, v82
	v_max3_f32 v36, v36, v83, v84
	v_max3_f32 v36, v36, v85, v86
	v_max3_f32 v36, v36, v87, v88
	v_max3_f32 v36, v36, v89, v90
	v_max3_f32 v36, v36, v91, v92
	v_max3_f32 v36, v36, v93, v94
	v_max3_f32 v36, v36, v95, v96
	v_max3_f32 v36, v36, v97, v98
	v_max3_f32 v36, v36, v99, v100
	v_max3_f32 v36, v36, v101, v102
	v_max3_f32 v36, v36, v103, v104
	v_max3_f32 v36, v36, v105, v106
	v_max3_f32 v36, v36, v107, v108
	v_max3_f32 v36, v36, v109, v110
	v_max3_f32 v36, v36, v111, v112
	v_max3_f32 v36, v36, v113, v114
	v_max3_f32 v36, v36, v115, v116
	v_max3_f32 v36, v36, v117, v118
	v_max3_f32 v36, v36, v119, v120
	v_max3_f32 v36, v36, v121, v122
	v_max3_f32 v36, v36, v123, v124
	v_max3_f32 v36, v36, v125, v126
	v_max3_f32 v36, v36, v127, v128
	v_max3_f32 v36, v36, v129, v130
	v_max3_f32 v36, v36, v131, v132
	v_max3_f32 v36, v36, v133, v134
	v_max3_f32 v36, v36, v135, v136
	v_max3_f32 v36, v36, v137, v138
	v_max3_f32 v36, v36, v139, v140
	v_max_f32_e32 v36, v36, v141
	v_mov_b32_e32 v37, v36
	s_nop 1
	v_permlane16_swap_b32_e32 v36, v37
	v_max_f32_e32 v36, v36, v37
	v_mov_b32_e32 v37, v36
	s_nop 1
	v_permlane32_swap_b32_e32 v36, v37
	v_max_f32_e32 v36, v36, v37
	v_mul_f32_e64 v38, v36, -v144
	v_mov_b32_e32 v40, 0
	v_mov_b32_e32 v41, 0
	v_mov_b32_e32 v39, v38
	v_pk_fma_f32 v[78:79], v[78:79], v[144:145], v[38:39]
	v_pk_fma_f32 v[80:81], v[80:81], v[144:145], v[38:39]
	v_exp_f32_e32 v78, v78
	v_exp_f32_e32 v79, v79
	v_exp_f32_e32 v80, v80
	v_exp_f32_e32 v81, v81
	v_pk_fma_f32 v[82:83], v[82:83], v[144:145], v[38:39]
	v_pk_fma_f32 v[84:85], v[84:85], v[144:145], v[38:39]
	v_exp_f32_e32 v82, v82
	v_exp_f32_e32 v83, v83
	v_exp_f32_e32 v84, v84
	v_exp_f32_e32 v85, v85
	v_pk_add_f32 v[40:41], v[40:41], v[78:79]
	v_pk_add_f32 v[40:41], v[40:41], v[80:81]
	v_pk_fma_f32 v[86:87], v[86:87], v[144:145], v[38:39]
	v_pk_fma_f32 v[88:89], v[88:89], v[144:145], v[38:39]
	v_exp_f32_e32 v86, v86
	v_exp_f32_e32 v87, v87
	v_exp_f32_e32 v88, v88
	v_exp_f32_e32 v89, v89
	v_pk_add_f32 v[40:41], v[40:41], v[82:83]
	v_pk_add_f32 v[40:41], v[40:41], v[84:85]
	v_pk_fma_f32 v[90:91], v[90:91], v[144:145], v[38:39]
	v_pk_fma_f32 v[92:93], v[92:93], v[144:145], v[38:39]
	v_exp_f32_e32 v90, v90
	v_exp_f32_e32 v91, v91
	v_exp_f32_e32 v92, v92
	v_exp_f32_e32 v93, v93
	v_pk_add_f32 v[40:41], v[40:41], v[86:87]
	v_pk_add_f32 v[40:41], v[40:41], v[88:89]
	v_pk_fma_f32 v[94:95], v[94:95], v[144:145], v[38:39]
	v_pk_fma_f32 v[96:97], v[96:97], v[144:145], v[38:39]
	v_exp_f32_e32 v94, v94
	v_exp_f32_e32 v95, v95
	v_exp_f32_e32 v96, v96
	v_exp_f32_e32 v97, v97
	v_pk_add_f32 v[40:41], v[40:41], v[90:91]
	v_pk_add_f32 v[40:41], v[40:41], v[92:93]
	v_pk_fma_f32 v[98:99], v[98:99], v[144:145], v[38:39]
	v_pk_fma_f32 v[100:101], v[100:101], v[144:145], v[38:39]
	v_exp_f32_e32 v98, v98
	v_exp_f32_e32 v99, v99
	v_exp_f32_e32 v100, v100
	v_exp_f32_e32 v101, v101
	v_pk_add_f32 v[40:41], v[40:41], v[94:95]
	v_pk_add_f32 v[40:41], v[40:41], v[96:97]
	v_pk_fma_f32 v[102:103], v[102:103], v[144:145], v[38:39]
	v_pk_fma_f32 v[104:105], v[104:105], v[144:145], v[38:39]
	v_exp_f32_e32 v102, v102
	v_exp_f32_e32 v103, v103
	v_exp_f32_e32 v104, v104
	v_exp_f32_e32 v105, v105
	v_pk_add_f32 v[40:41], v[40:41], v[98:99]
	v_pk_add_f32 v[40:41], v[40:41], v[100:101]
	v_pk_fma_f32 v[106:107], v[106:107], v[144:145], v[38:39]
	v_pk_fma_f32 v[108:109], v[108:109], v[144:145], v[38:39]
	v_exp_f32_e32 v106, v106
	v_exp_f32_e32 v107, v107
	v_exp_f32_e32 v108, v108
	v_exp_f32_e32 v109, v109
	v_pk_add_f32 v[40:41], v[40:41], v[102:103]
	v_pk_add_f32 v[40:41], v[40:41], v[104:105]
	v_pk_fma_f32 v[110:111], v[110:111], v[144:145], v[38:39]
	v_pk_fma_f32 v[112:113], v[112:113], v[144:145], v[38:39]
	v_exp_f32_e32 v110, v110
	v_exp_f32_e32 v111, v111
	v_exp_f32_e32 v112, v112
	v_exp_f32_e32 v113, v113
	v_pk_add_f32 v[40:41], v[40:41], v[106:107]
	v_pk_add_f32 v[40:41], v[40:41], v[108:109]
	v_pk_fma_f32 v[114:115], v[114:115], v[144:145], v[38:39]
	v_pk_fma_f32 v[116:117], v[116:117], v[144:145], v[38:39]
	v_exp_f32_e32 v114, v114
	v_exp_f32_e32 v115, v115
	v_exp_f32_e32 v116, v116
	v_exp_f32_e32 v117, v117
	v_pk_add_f32 v[40:41], v[40:41], v[110:111]
	v_pk_add_f32 v[40:41], v[40:41], v[112:113]
	v_pk_fma_f32 v[118:119], v[118:119], v[144:145], v[38:39]
	v_pk_fma_f32 v[120:121], v[120:121], v[144:145], v[38:39]
	v_exp_f32_e32 v118, v118
	v_exp_f32_e32 v119, v119
	v_exp_f32_e32 v120, v120
	v_exp_f32_e32 v121, v121
	v_pk_add_f32 v[40:41], v[40:41], v[114:115]
	v_pk_add_f32 v[40:41], v[40:41], v[116:117]
	v_pk_fma_f32 v[122:123], v[122:123], v[144:145], v[38:39]
	v_pk_fma_f32 v[124:125], v[124:125], v[144:145], v[38:39]
	v_exp_f32_e32 v122, v122
	v_exp_f32_e32 v123, v123
	v_exp_f32_e32 v124, v124
	v_exp_f32_e32 v125, v125
	v_pk_add_f32 v[40:41], v[40:41], v[118:119]
	v_pk_add_f32 v[40:41], v[40:41], v[120:121]
	v_pk_fma_f32 v[126:127], v[126:127], v[144:145], v[38:39]
	v_pk_fma_f32 v[128:129], v[128:129], v[144:145], v[38:39]
	v_exp_f32_e32 v126, v126
	v_exp_f32_e32 v127, v127
	v_exp_f32_e32 v128, v128
	v_exp_f32_e32 v129, v129
	v_pk_add_f32 v[40:41], v[40:41], v[122:123]
	v_pk_add_f32 v[40:41], v[40:41], v[124:125]
	v_pk_fma_f32 v[130:131], v[130:131], v[144:145], v[38:39]
	v_pk_fma_f32 v[132:133], v[132:133], v[144:145], v[38:39]
	v_exp_f32_e32 v130, v130
	v_exp_f32_e32 v131, v131
	v_exp_f32_e32 v132, v132
	v_exp_f32_e32 v133, v133
	v_pk_add_f32 v[40:41], v[40:41], v[126:127]
	v_pk_add_f32 v[40:41], v[40:41], v[128:129]
	v_pk_fma_f32 v[134:135], v[134:135], v[144:145], v[38:39]
	v_pk_fma_f32 v[136:137], v[136:137], v[144:145], v[38:39]
	v_exp_f32_e32 v134, v134
	v_exp_f32_e32 v135, v135
	v_exp_f32_e32 v136, v136
	v_exp_f32_e32 v137, v137
	v_pk_add_f32 v[40:41], v[40:41], v[130:131]
	v_pk_add_f32 v[40:41], v[40:41], v[132:133]
	v_pk_fma_f32 v[138:139], v[138:139], v[144:145], v[38:39]
	v_pk_fma_f32 v[140:141], v[140:141], v[144:145], v[38:39]
	v_exp_f32_e32 v138, v138
	v_exp_f32_e32 v139, v139
	v_exp_f32_e32 v140, v140
	v_exp_f32_e32 v141, v141
	v_pk_add_f32 v[40:41], v[40:41], v[134:135]
	v_pk_add_f32 v[40:41], v[40:41], v[136:137]
	s_nop 0
	v_pk_add_f32 v[40:41], v[40:41], v[138:139]
	v_pk_add_f32 v[40:41], v[40:41], v[140:141]
	v_add_f32_e32 v36, v40, v41
	v_mov_b32_e32 v37, v36
	s_nop 1
	v_permlane16_swap_b32_e32 v36, v37
	v_add_f32_e32 v36, v36, v37
	v_mov_b32_e32 v37, v36
	s_nop 1
	v_permlane32_swap_b32_e32 v36, v37
	v_add_f32_e32 v36, v36, v37
	v_rcp_f32_e32 v142, v36
	v_cvt_pk_bf16_f32 v78, v78, v79
	v_cvt_pk_bf16_f32 v79, v80, v81
	v_cvt_pk_bf16_f32 v80, v82, v83
	v_cvt_pk_bf16_f32 v81, v84, v85
	v_cvt_pk_bf16_f32 v86, v86, v87
	v_cvt_pk_bf16_f32 v87, v88, v89
	v_cvt_pk_bf16_f32 v88, v90, v91
	v_cvt_pk_bf16_f32 v89, v92, v93
	v_cvt_pk_bf16_f32 v94, v94, v95
	v_cvt_pk_bf16_f32 v95, v96, v97
	v_cvt_pk_bf16_f32 v96, v98, v99
	v_cvt_pk_bf16_f32 v97, v100, v101
	v_cvt_pk_bf16_f32 v102, v102, v103
	v_cvt_pk_bf16_f32 v103, v104, v105
	v_cvt_pk_bf16_f32 v104, v106, v107
	v_cvt_pk_bf16_f32 v105, v108, v109
	v_cvt_pk_bf16_f32 v110, v110, v111
	v_cvt_pk_bf16_f32 v111, v112, v113
	v_cvt_pk_bf16_f32 v112, v114, v115
	v_cvt_pk_bf16_f32 v113, v116, v117
	v_cvt_pk_bf16_f32 v118, v118, v119
	v_cvt_pk_bf16_f32 v119, v120, v121
	v_cvt_pk_bf16_f32 v120, v122, v123
	v_cvt_pk_bf16_f32 v121, v124, v125
	v_cvt_pk_bf16_f32 v126, v126, v127
	v_cvt_pk_bf16_f32 v127, v128, v129
	v_cvt_pk_bf16_f32 v128, v130, v131
	v_cvt_pk_bf16_f32 v129, v132, v133
	v_cvt_pk_bf16_f32 v134, v134, v135
	v_cvt_pk_bf16_f32 v135, v136, v137
	v_cvt_pk_bf16_f32 v136, v138, v139
	v_cvt_pk_bf16_f32 v137, v140, v141
	v_fma_f32 v143, -v36, v142, 1.0
	v_fma_f32 v142, v143, v142, v142
	v_mov_b32_e32 v143, v142
	ds_read_b64 v[82:83], v73 offset:53824
	ds_read_b64 v[84:85], v73 offset:53856
	s_waitcnt lgkmcnt(12)
	v_mfma_f32_16x16x32_bf16 v[32:35], v[48:51], v[78:81], 0
	ds_read_b64 v[90:91], v73 offset:62272
	ds_read_b64 v[92:93], v73 offset:62304
	s_waitcnt lgkmcnt(12)
	v_mfma_f32_16x16x32_bf16 v[36:39], v[52:55], v[78:81], 0
	ds_read_b64 v[48:49], v73 offset:36992
	ds_read_b64 v[50:51], v73 offset:37024
	s_waitcnt lgkmcnt(12)
	v_mfma_f32_16x16x32_bf16 v[40:43], v[56:59], v[78:81], 0
	ds_read_b64 v[52:53], v73 offset:45440
	ds_read_b64 v[54:55], v73 offset:45472
	s_waitcnt lgkmcnt(12)
	v_mfma_f32_16x16x32_bf16 v[44:47], v[60:63], v[78:81], 0
	ds_read_b64 v[56:57], v73 offset:53888
	ds_read_b64 v[58:59], v73 offset:53920
	s_waitcnt lgkmcnt(12)
	v_mfma_f32_16x16x32_bf16 v[32:35], v[64:67], v[86:89], v[32:35]
	ds_read_b64 v[60:61], v73 offset:62336
	ds_read_b64 v[62:63], v73 offset:62368
	s_waitcnt lgkmcnt(12)
	v_mfma_f32_16x16x32_bf16 v[36:39], v[68:71], v[86:89], v[36:39]
	ds_read_b64 v[64:65], v73 offset:37056
	ds_read_b64 v[66:67], v73 offset:37088
	s_waitcnt lgkmcnt(12)
	v_mfma_f32_16x16x32_bf16 v[40:43], v[82:85], v[86:89], v[40:43]
	ds_read_b64 v[68:69], v73 offset:45504
	ds_read_b64 v[70:71], v73 offset:45536
	s_waitcnt lgkmcnt(12)
	v_mfma_f32_16x16x32_bf16 v[44:47], v[90:93], v[86:89], v[44:47]
	ds_read_b64 v[82:83], v73 offset:53952
	ds_read_b64 v[84:85], v73 offset:53984
	s_waitcnt lgkmcnt(12)
	v_mfma_f32_16x16x32_bf16 v[32:35], v[48:51], v[94:97], v[32:35]
	ds_read_b64 v[90:91], v73 offset:62400
	ds_read_b64 v[92:93], v73 offset:62432
	s_waitcnt lgkmcnt(12)
	v_mfma_f32_16x16x32_bf16 v[36:39], v[52:55], v[94:97], v[36:39]
	ds_read_b64 v[48:49], v73 offset:37120
	ds_read_b64 v[50:51], v73 offset:37152
	s_waitcnt lgkmcnt(12)
	v_mfma_f32_16x16x32_bf16 v[40:43], v[56:59], v[94:97], v[40:43]
	ds_read_b64 v[52:53], v73 offset:45568
	ds_read_b64 v[54:55], v73 offset:45600
	s_waitcnt lgkmcnt(12)
	v_mfma_f32_16x16x32_bf16 v[44:47], v[60:63], v[94:97], v[44:47]
	ds_read_b64 v[56:57], v73 offset:54016
	ds_read_b64 v[58:59], v73 offset:54048
	s_waitcnt lgkmcnt(12)
	v_mfma_f32_16x16x32_bf16 v[32:35], v[64:67], v[102:105], v[32:35]
	ds_read_b64 v[60:61], v73 offset:62464
	ds_read_b64 v[62:63], v73 offset:62496
	s_waitcnt lgkmcnt(12)
	v_mfma_f32_16x16x32_bf16 v[36:39], v[68:71], v[102:105], v[36:39]
	ds_read_b64 v[64:65], v73 offset:37184
	ds_read_b64 v[66:67], v73 offset:37216
	s_waitcnt lgkmcnt(12)
	v_mfma_f32_16x16x32_bf16 v[40:43], v[82:85], v[102:105], v[40:43]
	ds_read_b64 v[68:69], v73 offset:45632
	ds_read_b64 v[70:71], v73 offset:45664
	s_waitcnt lgkmcnt(12)
	v_mfma_f32_16x16x32_bf16 v[44:47], v[90:93], v[102:105], v[44:47]
	ds_read_b64 v[82:83], v73 offset:54080
	ds_read_b64 v[84:85], v73 offset:54112
	s_waitcnt lgkmcnt(12)
	v_mfma_f32_16x16x32_bf16 v[32:35], v[48:51], v[110:113], v[32:35]
	ds_read_b64 v[90:91], v73 offset:62528
	ds_read_b64 v[92:93], v73 offset:62560
	s_waitcnt lgkmcnt(12)
	v_mfma_f32_16x16x32_bf16 v[36:39], v[52:55], v[110:113], v[36:39]
	ds_read_b64 v[48:49], v73 offset:37248
	ds_read_b64 v[50:51], v73 offset:37280
	s_waitcnt lgkmcnt(12)
	v_mfma_f32_16x16x32_bf16 v[40:43], v[56:59], v[110:113], v[40:43]
	ds_read_b64 v[52:53], v73 offset:45696
	ds_read_b64 v[54:55], v73 offset:45728
	s_waitcnt lgkmcnt(12)
	v_mfma_f32_16x16x32_bf16 v[44:47], v[60:63], v[110:113], v[44:47]
	ds_read_b64 v[56:57], v73 offset:54144
	ds_read_b64 v[58:59], v73 offset:54176
	s_waitcnt lgkmcnt(12)
	v_mfma_f32_16x16x32_bf16 v[32:35], v[64:67], v[118:121], v[32:35]
	ds_read_b64 v[60:61], v73 offset:62592
	ds_read_b64 v[62:63], v73 offset:62624
	s_waitcnt lgkmcnt(12)
	v_mfma_f32_16x16x32_bf16 v[36:39], v[68:71], v[118:121], v[36:39]
	ds_read_b64 v[64:65], v73 offset:37312
	ds_read_b64 v[66:67], v73 offset:37344
	s_waitcnt lgkmcnt(12)
	v_mfma_f32_16x16x32_bf16 v[40:43], v[82:85], v[118:121], v[40:43]
	ds_read_b64 v[68:69], v73 offset:45760
	ds_read_b64 v[70:71], v73 offset:45792
	s_waitcnt lgkmcnt(12)
	v_mfma_f32_16x16x32_bf16 v[44:47], v[90:93], v[118:121], v[44:47]
	ds_read_b64 v[82:83], v73 offset:54208
	ds_read_b64 v[84:85], v73 offset:54240
	s_waitcnt lgkmcnt(12)
	v_mfma_f32_16x16x32_bf16 v[32:35], v[48:51], v[126:129], v[32:35]
	ds_read_b64 v[90:91], v73 offset:62656
	ds_read_b64 v[92:93], v73 offset:62688
	s_waitcnt lgkmcnt(12)
	v_mfma_f32_16x16x32_bf16 v[36:39], v[52:55], v[126:129], v[36:39]
	s_waitcnt lgkmcnt(10)
	v_mfma_f32_16x16x32_bf16 v[40:43], v[56:59], v[126:129], v[40:43]
	s_waitcnt lgkmcnt(8)
	v_mfma_f32_16x16x32_bf16 v[44:47], v[60:63], v[126:129], v[44:47]
	s_waitcnt lgkmcnt(6)
	v_mfma_f32_16x16x32_bf16 v[32:35], v[64:67], v[134:137], v[32:35]
	s_waitcnt lgkmcnt(4)
	v_mfma_f32_16x16x32_bf16 v[36:39], v[68:71], v[134:137], v[36:39]
	s_waitcnt lgkmcnt(2)
	v_mfma_f32_16x16x32_bf16 v[40:43], v[82:85], v[134:137], v[40:43]
	s_waitcnt lgkmcnt(0)
	v_mfma_f32_16x16x32_bf16 v[44:47], v[90:93], v[134:137], v[44:47]
	s_add_u32 s16, s12, 0x88000
	s_addc_u32 s17, s13, 0
	s_nop 7
	v_pk_mul_f32 v[32:33], v[32:33], v[142:143]
	v_pk_mul_f32 v[34:35], v[34:35], v[142:143]
	v_pk_mul_f32 v[36:37], v[36:37], v[142:143]
	v_pk_mul_f32 v[38:39], v[38:39], v[142:143]
	v_pk_mul_f32 v[40:41], v[40:41], v[142:143]
	v_pk_mul_f32 v[42:43], v[42:43], v[142:143]
	v_pk_mul_f32 v[44:45], v[44:45], v[142:143]
	v_pk_mul_f32 v[46:47], v[46:47], v[142:143]
	v_cvt_pk_bf16_f32 v32, v32, v33
	v_cvt_pk_bf16_f32 v33, v34, v35
	v_cvt_pk_bf16_f32 v36, v36, v37
	v_cvt_pk_bf16_f32 v37, v38, v39
	v_cvt_pk_bf16_f32 v40, v40, v41
	v_cvt_pk_bf16_f32 v41, v42, v43
	v_cvt_pk_bf16_f32 v44, v44, v45
	v_cvt_pk_bf16_f32 v45, v46, v47
	global_store_dwordx2 v74, v[32:33], s[16:17] offset:0
	global_store_dwordx2 v74, v[36:37], s[16:17] offset:32
	global_store_dwordx2 v74, v[40:41], s[16:17] offset:64
	global_store_dwordx2 v74, v[44:45], s[16:17] offset:96
	s_cmp_eq_u32 m0, 0x1234
	s_cbranch_scc1 .Latt_late_ret
	s_branch .LBB0_270

.LBB0_292:
	s_cmp_eq_u32 m0, 0x5a5a5a5a
	s_cbranch_scc0 .Latt_late_ret
	s_mov_b32 m0, 0
	s_branch .Lmyatt_late
